# f1, f3 and merge-gate GEMMs: LDS-DMA destination m0 formed as s_add_u32 m0, wave_base_sgpr, const instead of v_add + v_readfirstlane + s_mov (48 sites, 18 dead adds removed)
# speedup vs baseline: 1.0065x; 1.0065x over previous
; DI void lds_barrier() { asm volatile("s_waitcnt lgkmcnt(0)\n\ts_barrier" ::: "memory"); }
; DI int tid512() { int t = threadIdx.x; asm volatile("" : "+v"(t)); return t; }
; #define G_WAIT_V(n) asm volatile("s_waitcnt vmcnt(" #n ")" ::: "memory")
; #define G_BAR __builtin_amdgcn_s_barrier()
;     ...
;   const int t = tid512();
;   const int wid = t >> 6, lane = t & 63, wr = wid >> 2, wc = wid & 3, fr = lane & 15, fq = lane >> 4;
;   int r0, c0, r1, c1;
;   g_stage_rc(t * 16, r0, c0); g_stage_rc(t * 16 + 8192, r1, c1);
;   const int oa0 = r0 * LDA + c0, oa1 = r1 * LDA + c1, ob0 = r0 * LDB + c0, ob1 = r1 * LDB + c1;
;   const int obr = fr * 64 + fq * 16, rdo = obr ^ (((obr >> 9) & 1) << 5);
;   bf16x8 At[4][2], B0[2][2], B1[2][2];
;   constexpr int nt = K / 64;
;   lds_barrier();
;   G_STAGE(G_SB(0, 0), B, ob0, ob1, LDB, 0, KB(0)); G_STAGE(G_SA(0, 0), A, oa0, oa1, LDA, 0, KA(0));
;   G_STAGE(G_SB(0, 1), B, ob0, ob1, LDB, 128, KB(0)); G_STAGE(G_SA(0, 1), A, oa0, oa1, LDA, 128, KA(0));
;   if (wr == 1) G_BAR;
;   G_WAIT_V(4); G_BAR;
;   G_STAGE(G_SB(1, 0), B, ob0, ob1, LDB, 0, KB(1)); G_STAGE(G_SA(1, 0), A, oa0, oa1, LDA, 0, KA(1)); G_STAGE(G_SB(1, 1), B, ob0, ob1, LDB, 128, KB(1));
;   G_WAIT_V(6); G_BAR;
; DI bool xcd_tile256(int k, int NT, int& m, int& n) {
;   const int x = blockIdx.x & 7, slots = gridDim.x >> 3;
;   const int idx = (int)(blockIdx.x >> 3) + slots * k;
;   if (idx >= 16 * NT) return false;
;   const int mg = idx / (8 * NT), rem = idx - mg * 8 * NT;
;   n = rem >> 3; m = x * 16 + mg * 8 + (rem & 7);
;   return true;
; }
.LBB0_37:
	s_lshr_b32 s0, s16, 2
	s_and_b32 s36, s0, 8
	s_lshl_b32 s0, s36, 2
	s_sub_i32 s0, s16, s0
	s_and_b32 s37, s16, 7
	s_ashr_i32 s18, s0, 3
	s_or_b32 s0, s37, s47
	v_mov_b32_e32 v0, v168
	s_or_b32 s35, s0, s36
	s_lshl_b32 s0, s35, 19
	v_lshlrev_b32_e32 v143, 4, v0
	s_nop 0
	v_readfirstlane_b32 s32, v143
	v_and_b32_e32 v2, 32, v0
	v_lshrrev_b32_e32 v4, 1, v0
	v_bitop3_b32 v2, v143, v2, 48 bitop3:0x6c
	s_add_u32 s16, s8, s0
	v_ashrrev_i32_e32 v10, 3, v0
	v_bfe_u32 v13, v0, 2, 4
	s_mov_b32 s0, 0x3ffff0
	v_and_b32_e32 v11, 32, v4
	v_lshrrev_b32_e32 v12, 1, v2
	v_add_u32_e32 v144, 0x2000, v143
	s_addc_u32 s17, s9, 0
	s_ashr_i32 s19, s18, 31
	v_and_or_b32 v3, v10, s0, v13
	v_or_b32_e32 v2, v12, v11
	v_ashrrev_i32_e32 v15, 7, v144
	s_lshl_b64 s[20:21], s[18:19], 19
	v_and_or_b32 v4, v15, s0, v13
	v_lshl_or_b32 v132, v3, 10, v2
	s_add_u32 s22, s28, s20
	v_lshl_or_b32 v130, v4, 10, v2
	v_ashrrev_i32_e32 v133, 31, v132
	v_add_u32_e32 v146, 0x10000, v143
	s_addc_u32 s23, s29, s21
	v_lshlrev_b64 v[16:17], 1, v[132:133]
	v_readfirstlane_b32 s0, v146
	v_ashrrev_i32_e32 v131, 31, v130
	v_add_u32_e32 v147, 0x12000, v143
	s_waitcnt lgkmcnt(0)
	s_barrier
	v_lshl_add_u64 v[2:3], s[22:23], 0, v[16:17]
	s_mov_b32 m0, s0
	v_lshlrev_b64 v[18:19], 1, v[130:131]
	v_readfirstlane_b32 s0, v147
	global_load_lds_dwordx4 v[2:3], off
	v_lshl_add_u64 v[6:7], s[22:23], 0, v[18:19]
	s_mov_b32 m0, s0
	s_nop 0
	global_load_lds_dwordx4 v[6:7], off
	v_lshl_add_u64 v[8:9], s[16:17], 0, v[16:17]
	s_mov_b32 m0, s32
	s_nop 0
	global_load_lds_dwordx4 v[8:9], off
	s_add_u32 m0, s32, 0x2000
	s_add_u32 s0, s22, 0x40000
	v_add_u32_e32 v148, 0x14000, v143
	v_lshl_add_u64 v[4:5], s[16:17], 0, v[18:19]
	s_addc_u32 s1, s23, 0
	v_readfirstlane_b32 s24, v148
	global_load_lds_dwordx4 v[4:5], off
	v_lshl_add_u64 v[20:21], s[0:1], 0, v[16:17]
	s_mov_b32 m0, s24
	v_add_u32_e32 v149, 0x16000, v143
	global_load_lds_dwordx4 v[20:21], off
	v_lshl_add_u64 v[20:21], s[0:1], 0, v[18:19]
	v_readfirstlane_b32 s0, v149
	s_mov_b32 m0, s0
	s_add_u32 s0, s16, 0x40000
	s_addc_u32 s1, s17, 0
	global_load_lds_dwordx4 v[20:21], off
	v_lshl_add_u64 v[16:17], s[0:1], 0, v[16:17]
	s_add_u32 m0, s32, 0x4000
	v_add_u32_e32 v152, 0x6000, v143
	global_load_lds_dwordx4 v[16:17], off
	v_lshl_add_u64 v[16:17], s[0:1], 0, v[18:19]
	v_readfirstlane_b32 s0, v152
	s_mov_b32 m0, s0
	v_ashrrev_i32_e32 v14, 8, v0
	global_load_lds_dwordx4 v[16:17], off
	v_cmp_eq_u32_e32 vcc, 1, v14
	s_and_saveexec_b64 s[24:25], vcc
	s_cbranch_execz .LBB0_39
	s_barrier
.LBB0_39:
	s_or_b64 exec, exec, s[24:25]
	v_add_u32_e32 v153, 0x18000, v143
	v_add_u32_e32 v154, 0x1a000, v143
	v_readfirstlane_b32 s0, v153
	v_lshl_add_u64 v[2:3], v[2:3], 0, s[76:77]
	s_mov_b32 m0, s0
	v_readfirstlane_b32 s0, v154
	v_add_u32_e32 v155, 0x8000, v143
	s_waitcnt vmcnt(4)
	s_barrier
	global_load_lds_dwordx4 v[2:3], off
	v_lshl_add_u64 v[2:3], v[6:7], 0, s[76:77]
	s_mov_b32 m0, s0
	v_readfirstlane_b32 s0, v155
	global_load_lds_dwordx4 v[2:3], off
	v_lshl_add_u64 v[2:3], v[8:9], 0, s[76:77]
	s_mov_b32 m0, s0
	s_nop 0
	global_load_lds_dwordx4 v[2:3], off
	s_add_u32 m0, s32, 0xa000
	s_add_u32 s0, s22, 0x40080
	v_lshl_add_u64 v[2:3], v[4:5], 0, s[76:77]
	s_addc_u32 s1, s23, 0
	global_load_lds_dwordx4 v[2:3], off
	v_lshl_add_u64 v[2:3], v[132:133], 1, s[0:1]
	s_add_u32 m0, s32, 0x1c000
	s_nop 0
	global_load_lds_dwordx4 v[2:3], off
	v_lshl_add_u64 v[2:3], v[130:131], 1, s[0:1]
	s_add_u32 m0, s32, 0x1e000
	v_lshlrev_b32_e32 v17, 6, v0
	global_load_lds_dwordx4 v[2:3], off
	v_and_b32_e32 v16, 48, v0
	v_and_b32_e32 v18, 0x3c0, v17
	v_lshlrev_b32_e32 v20, 2, v0
	v_or_b32_e32 v19, v18, v16
	v_and_b32_e32 v20, 32, v20
	s_mov_b32 s0, 0x14000
	v_bitop3_b32 v8, v19, s0, v20 bitop3:0xde
	s_mov_b32 s0, 0x18000
	v_bitop3_b32 v9, v19, s0, v20 bitop3:0xde
	s_mov_b32 s0, 0x1c000
	v_lshlrev_b32_e32 v2, 10, v15
	v_lshlrev_b32_e32 v5, 10, v10
	v_lshlrev_b32_e32 v7, 13, v14
	v_bitop3_b32 v14, v19, s0, v20 bitop3:0xde
	s_add_i32 s0, s47, s36
	v_and_b32_e32 v2, 0xffffc000, v2
	v_lshlrev_b32_e32 v4, 10, v13
	v_and_b32_e32 v5, 0xffffc000, v5
	s_add_i32 s0, s0, s37
	v_or3_b32 v2, v12, v2, v4
	v_or3_b32 v4, v12, v5, v4
	s_lshl_b32 s0, s0, 19
	v_add_u32_e32 v2, v2, v11
	v_add_u32_e32 v4, v4, v11
	v_ashrrev_i32_e32 v3, 31, v2
	s_add_u32 s0, s8, s0
	v_ashrrev_i32_e32 v5, 31, v4
	v_lshlrev_b64 v[2:3], 1, v[2:3]
	s_addc_u32 s1, s9, 0
	v_lshlrev_b64 v[4:5], 1, v[4:5]
	v_lshl_add_u64 v[134:135], s[0:1], 0, v[2:3]
	v_lshl_add_u64 v[136:137], s[0:1], 0, v[4:5]
	s_add_u32 s0, s26, s20
	s_waitcnt vmcnt(6)
; #define G_LDA(dst, b, h)                                                                                                  \
;   _Pragma("unroll") for (int m = 0; m < 4; ++m) _Pragma("unroll") for (int k = 0; k < 2; ++k)                             \
;       dst[m][k] = *(const bf16x8*)((const char*)G_SA(b, h) + ((wr * 4 + m) * 2 + k) * 1024 + rdo)
; #define G_LDB(dst, b, h)                                                                                                  \
;   _Pragma("unroll") for (int n = 0; n < 2; ++n) _Pragma("unroll") for (int k = 0; k < 2; ++k)                             \
;       dst[n][k] = *(const bf16x8*)((const char*)G_SB(b, h) + ((wc * 2 + n) * 2 + k) * 1024 + rdo)
; #define G_WAIT_L(n) asm volatile("s_waitcnt lgkmcnt(" #n ")" ::: "memory")
; #define G_BAR __builtin_amdgcn_s_barrier()
; #define G_SCHED __builtin_amdgcn_sched_barrier(0)
;     ...
;   for (int tt = 0; tt < nt - 2; tt += 2) {
;     G_LDB(B0, 0, 0); G_SCHED; G_LDA(At, 0, 0); G_STAGE(G_SA(1, 1), A, oa0, oa1, LDA, 128, KA(tt + 1));
;     G_WAIT_L(8); G_BAR; G_WAIT_L(0); G_MMA(0, 0, At, B0); G_BAR; G_SCHED;
; DI void zero_acc256(f32x4 (&a)[2][2][4][2]) {
; #pragma unroll
;   for (int i = 0; i < 2; ++i)
; #pragma unroll
;     for (int j = 0; j < 2; ++j)
; #pragma unroll
;       for (int m = 0; m < 4; ++m)
; #pragma unroll
;         for (int n = 0; n < 2; ++n)
; #pragma unroll
;           for (int e = 0; e < 4; ++e) a[i][j][m][n][e] = 0.f;
; }
	s_addc_u32 s1, s27, s21
	v_bitop3_b32 v16, v18, v20, v16 bitop3:0x36
	v_bitop3_b32 v6, v19, s88, v20 bitop3:0xde
	v_and_b32_e32 v17, 0x3000, v17
	v_lshl_add_u64 v[138:139], s[0:1], 0, v[2:3]
	v_mov_b32_e32 v2, 0
	v_lshl_add_u64 v[140:141], s[0:1], 0, v[4:5]
	s_mov_b32 s22, -2
	s_mov_b64 s[20:21], 0
	v_add_u32_e32 v162, v6, v17
	v_add_u32_e32 v142, v16, v7
	v_add_u32_e32 v159, v8, v17
	v_add_u32_e32 v150, v9, v17
	v_add_u32_e32 v145, v14, v17
	v_mov_b32_e32 v3, v2
	v_mov_b32_e32 v4, v2
	v_mov_b32_e32 v5, v2
	v_mov_b32_e32 v6, v2
	v_mov_b32_e32 v7, v2
	v_mov_b32_e32 v8, v2
	v_mov_b32_e32 v9, v2
	v_mov_b32_e32 v10, v2
	v_mov_b32_e32 v11, v2
	v_mov_b32_e32 v12, v2
	v_mov_b32_e32 v13, v2
	v_mov_b32_e32 v14, v2
	v_mov_b32_e32 v15, v2
	v_mov_b32_e32 v16, v2
	v_mov_b32_e32 v17, v2
	v_mov_b32_e32 v18, v2
	v_mov_b32_e32 v19, v2
	v_mov_b32_e32 v20, v2
	v_mov_b32_e32 v21, v2
	v_mov_b32_e32 v22, v2
	v_mov_b32_e32 v23, v2
	v_mov_b32_e32 v24, v2
	v_mov_b32_e32 v25, v2
	v_mov_b32_e32 v26, v2
	v_mov_b32_e32 v27, v2
	v_mov_b32_e32 v28, v2
	v_mov_b32_e32 v29, v2
	v_mov_b32_e32 v30, v2
	v_mov_b32_e32 v31, v2
	v_mov_b32_e32 v32, v2
	v_mov_b32_e32 v33, v2
	v_mov_b32_e32 v34, v2
	v_mov_b32_e32 v35, v2
	v_mov_b32_e32 v36, v2
	v_mov_b32_e32 v37, v2
	v_mov_b32_e32 v38, v2
	v_mov_b32_e32 v39, v2
	v_mov_b32_e32 v40, v2
	v_mov_b32_e32 v41, v2
	v_mov_b32_e32 v42, v2
	v_mov_b32_e32 v43, v2
	v_mov_b32_e32 v44, v2
	v_mov_b32_e32 v45, v2
	v_mov_b32_e32 v46, v2
	v_mov_b32_e32 v47, v2
	v_mov_b32_e32 v48, v2
	v_mov_b32_e32 v49, v2
	v_mov_b32_e32 v50, v2
	v_mov_b32_e32 v51, v2
	v_mov_b32_e32 v52, v2
	v_mov_b32_e32 v53, v2
	v_mov_b32_e32 v54, v2
	v_mov_b32_e32 v55, v2
	v_mov_b32_e32 v56, v2
	v_mov_b32_e32 v57, v2
	v_mov_b32_e32 v62, v2
	v_mov_b32_e32 v63, v2
	v_mov_b32_e32 v64, v2
	v_mov_b32_e32 v65, v2
	v_mov_b32_e32 v78, v2
	v_mov_b32_e32 v79, v2
	v_mov_b32_e32 v80, v2
	v_mov_b32_e32 v81, v2
	v_mov_b32_e32 v94, v2
	v_mov_b32_e32 v95, v2
	v_mov_b32_e32 v96, v2
	v_mov_b32_e32 v97, v2
	v_mov_b32_e32 v98, v2
	v_mov_b32_e32 v99, v2
	v_mov_b32_e32 v100, v2
	v_mov_b32_e32 v101, v2
	v_mov_b32_e32 v102, v2
	v_mov_b32_e32 v103, v2
	v_mov_b32_e32 v104, v2
	v_mov_b32_e32 v105, v2
	v_mov_b32_e32 v106, v2
	v_mov_b32_e32 v107, v2
	v_mov_b32_e32 v108, v2
	v_mov_b32_e32 v109, v2
	v_mov_b32_e32 v110, v2
	v_mov_b32_e32 v111, v2
	v_mov_b32_e32 v112, v2
	v_mov_b32_e32 v113, v2
	v_mov_b32_e32 v114, v2
	v_mov_b32_e32 v115, v2
	v_mov_b32_e32 v116, v2
	v_mov_b32_e32 v117, v2
	v_mov_b32_e32 v118, v2
	v_mov_b32_e32 v119, v2
	v_mov_b32_e32 v120, v2
	v_mov_b32_e32 v121, v2
	v_mov_b32_e32 v122, v2
	v_mov_b32_e32 v123, v2
	v_mov_b32_e32 v124, v2
	v_mov_b32_e32 v125, v2
	v_mov_b32_e32 v126, v2
	v_mov_b32_e32 v127, v2
	v_mov_b32_e32 v128, v2
	v_mov_b32_e32 v129, v2
	v_mov_b32_e32 v58, v2
	v_mov_b32_e32 v59, v2
	v_mov_b32_e32 v60, v2
	v_mov_b32_e32 v61, v2
	v_mov_b32_e32 v66, v2
	v_mov_b32_e32 v67, v2
	v_mov_b32_e32 v68, v2
	v_mov_b32_e32 v69, v2
	v_mov_b32_e32 v70, v2
	v_mov_b32_e32 v71, v2
	v_mov_b32_e32 v72, v2
	v_mov_b32_e32 v73, v2
	v_mov_b32_e32 v74, v2
	v_mov_b32_e32 v75, v2
	v_mov_b32_e32 v76, v2
	v_mov_b32_e32 v77, v2
	v_mov_b32_e32 v82, v2
	v_mov_b32_e32 v83, v2
	v_mov_b32_e32 v84, v2
	v_mov_b32_e32 v85, v2
	v_mov_b32_e32 v86, v2
	v_mov_b32_e32 v87, v2
	v_mov_b32_e32 v88, v2
	v_mov_b32_e32 v89, v2
	v_mov_b32_e32 v90, v2
	v_mov_b32_e32 v91, v2
	v_mov_b32_e32 v92, v2
	v_mov_b32_e32 v93, v2
	s_mov_b64 s[24:25], 0x12f0100
	s_mov_b64 s[36:37], 0x12b0180
	s_mov_b64 s[40:41], 0x12f0180
	s_barrier
.LBB0_40:
	ds_read_b128 v[164:167], v162
	ds_read_b128 v[182:185], v162 offset:1024
	ds_read_b128 v[186:189], v162 offset:2048
	ds_read_b128 v[190:193], v162 offset:3072
	v_lshl_add_u64 v[242:243], v[136:137], 0, s[20:21]
	v_lshl_add_u64 v[226:227], v[242:243], 0, s[78:79]
	s_add_u32 m0, s32, 0xc000
	v_lshl_add_u64 v[244:245], v[134:135], 0, s[20:21]
	ds_read_b128 v[194:197], v142
	ds_read_b128 v[198:201], v142 offset:1024
	ds_read_b128 v[202:205], v142 offset:2048
	ds_read_b128 v[206:209], v142 offset:3072
	ds_read_b128 v[210:213], v142 offset:4096
	ds_read_b128 v[214:217], v142 offset:5120
	ds_read_b128 v[218:221], v142 offset:6144
	ds_read_b128 v[222:225], v142 offset:7168
	global_load_lds_dwordx4 v[226:227], off
	s_add_u32 m0, s32, 0xe000
	v_lshl_add_u64 v[226:227], v[244:245], 0, s[78:79]
	global_load_lds_dwordx4 v[226:227], off
	s_waitcnt lgkmcnt(8)
	s_barrier
	s_waitcnt lgkmcnt(0)
	v_mfma_f32_16x16x32_bf16 v[126:129], v[194:197], v[164:167], v[126:129]
	v_mfma_f32_16x16x32_bf16 v[122:125], v[194:197], v[186:189], v[122:125]
	v_mfma_f32_16x16x32_bf16 v[118:121], v[202:205], v[164:167], v[118:121]
	v_mfma_f32_16x16x32_bf16 v[114:117], v[202:205], v[186:189], v[114:117]
	v_mfma_f32_16x16x32_bf16 v[110:113], v[210:213], v[164:167], v[110:113]
	v_mfma_f32_16x16x32_bf16 v[106:109], v[210:213], v[186:189], v[106:109]
	v_mfma_f32_16x16x32_bf16 v[102:105], v[218:221], v[164:167], v[102:105]
	v_mfma_f32_16x16x32_bf16 v[98:101], v[218:221], v[186:189], v[98:101]
	v_mfma_f32_16x16x32_bf16 v[126:129], v[198:201], v[182:185], v[126:129]
	v_mfma_f32_16x16x32_bf16 v[122:125], v[198:201], v[190:193], v[122:125]
	v_mfma_f32_16x16x32_bf16 v[118:121], v[206:209], v[182:185], v[118:121]
	v_mfma_f32_16x16x32_bf16 v[114:117], v[206:209], v[190:193], v[114:117]
	v_mfma_f32_16x16x32_bf16 v[110:113], v[214:217], v[182:185], v[110:113]
	v_mfma_f32_16x16x32_bf16 v[106:109], v[214:217], v[190:193], v[106:109]
	v_mfma_f32_16x16x32_bf16 v[102:105], v[222:225], v[182:185], v[102:105]
	v_mfma_f32_16x16x32_bf16 v[98:101], v[222:225], v[190:193], v[98:101]
	s_barrier
; #define G_LDA(dst, b, h)                                                                                                  \
;   _Pragma("unroll") for (int m = 0; m < 4; ++m) _Pragma("unroll") for (int k = 0; k < 2; ++k)                             \
;       dst[m][k] = *(const bf16x8*)((const char*)G_SA(b, h) + ((wr * 4 + m) * 2 + k) * 1024 + rdo)
; #define G_LDB(dst, b, h)                                                                                                  \
;   _Pragma("unroll") for (int n = 0; n < 2; ++n) _Pragma("unroll") for (int k = 0; k < 2; ++k)                             \
;       dst[n][k] = *(const bf16x8*)((const char*)G_SB(b, h) + ((wc * 2 + n) * 2 + k) * 1024 + rdo)
; #define G_WAIT_V(n) asm volatile("s_waitcnt vmcnt(" #n ")" ::: "memory")
; #define G_WAIT_L(n) asm volatile("s_waitcnt lgkmcnt(" #n ")" ::: "memory")
; #define G_BAR __builtin_amdgcn_s_barrier()
; #define G_SCHED __builtin_amdgcn_sched_barrier(0)
;     ...
;     G_WAIT_L(8); G_BAR; G_WAIT_L(0); G_MMA(0, 0, At, B0); G_BAR; G_SCHED;
;     G_LDB(B1, 0, 1); G_STAGE(G_SB(0, 0), B, ob0, ob1, LDB, 0, KB(tt + 2));
;     G_BAR; G_WAIT_L(0); G_MMA(0, 1, At, B1); G_BAR;
;     G_LDA(At, 0, 1); G_STAGE(G_SA(0, 0), A, oa0, oa1, LDA, 0, KA(tt + 2));
;     G_BAR; G_WAIT_L(0); G_MMA(1, 0, At, B0); G_BAR; G_SCHED;
;     G_STAGE(G_SB(0, 1), B, ob0, ob1, LDB, 128, KB(tt + 2));
;     G_WAIT_V(6); G_BAR; G_MMA(1, 1, At, B1); G_BAR;
;     G_LDB(B0, 1, 0); G_SCHED; G_LDA(At, 1, 0); G_STAGE(G_SA(0, 1), A, oa0, oa1, LDA, 128, KA(tt + 2));
	v_lshl_add_u64 v[246:247], v[140:141], 0, s[20:21]
	v_readfirstlane_b32 s0, v146
	v_lshl_add_u64 v[248:249], v[246:247], 0, s[42:43]
	s_mov_b32 m0, s0
	ds_read_b128 v[226:229], v159
	ds_read_b128 v[230:233], v159 offset:1024
	ds_read_b128 v[234:237], v159 offset:2048
	ds_read_b128 v[238:241], v159 offset:3072
	global_load_lds_dwordx4 v[248:249], off
	v_lshl_add_u64 v[248:249], v[138:139], 0, s[20:21]
	v_readfirstlane_b32 s0, v147
	s_mov_b32 m0, s0
	v_lshl_add_u64 v[250:251], v[248:249], 0, s[42:43]
	global_load_lds_dwordx4 v[250:251], off
	s_barrier
	s_waitcnt lgkmcnt(0)
	v_mfma_f32_16x16x32_bf16 v[94:97], v[194:197], v[226:229], v[94:97]
	v_mfma_f32_16x16x32_bf16 v[78:81], v[194:197], v[234:237], v[78:81]
	v_mfma_f32_16x16x32_bf16 v[62:65], v[202:205], v[226:229], v[62:65]
	v_mfma_f32_16x16x32_bf16 v[54:57], v[202:205], v[234:237], v[54:57]
	v_mfma_f32_16x16x32_bf16 v[50:53], v[210:213], v[226:229], v[50:53]
	v_mfma_f32_16x16x32_bf16 v[46:49], v[210:213], v[234:237], v[46:49]
	v_mfma_f32_16x16x32_bf16 v[42:45], v[218:221], v[226:229], v[42:45]
	v_mfma_f32_16x16x32_bf16 v[38:41], v[218:221], v[234:237], v[38:41]
	v_mfma_f32_16x16x32_bf16 v[94:97], v[198:201], v[230:233], v[94:97]
	v_mfma_f32_16x16x32_bf16 v[78:81], v[198:201], v[238:241], v[78:81]
	v_mfma_f32_16x16x32_bf16 v[62:65], v[206:209], v[230:233], v[62:65]
	v_mfma_f32_16x16x32_bf16 v[54:57], v[206:209], v[238:241], v[54:57]
	v_mfma_f32_16x16x32_bf16 v[50:53], v[214:217], v[230:233], v[50:53]
	v_mfma_f32_16x16x32_bf16 v[46:49], v[214:217], v[238:241], v[46:49]
	v_mfma_f32_16x16x32_bf16 v[42:45], v[222:225], v[230:233], v[42:45]
	v_mfma_f32_16x16x32_bf16 v[38:41], v[222:225], v[238:241], v[38:41]
	v_lshl_add_u64 v[250:251], v[242:243], 0, s[82:83]
	s_mov_b32 m0, s32
	s_barrier
	ds_read_b128 v[194:197], v142 offset:16384
	ds_read_b128 v[198:201], v142 offset:17408
	ds_read_b128 v[202:205], v142 offset:18432
	ds_read_b128 v[206:209], v142 offset:19456
	ds_read_b128 v[210:213], v142 offset:20480
	ds_read_b128 v[214:217], v142 offset:21504
	ds_read_b128 v[218:221], v142 offset:22528
	ds_read_b128 v[222:225], v142 offset:23552
	global_load_lds_dwordx4 v[250:251], off
	s_add_u32 m0, s32, 0x2000
	v_lshl_add_u64 v[250:251], v[244:245], 0, s[82:83]
	global_load_lds_dwordx4 v[250:251], off
	s_barrier
	s_waitcnt lgkmcnt(0)
	v_mfma_f32_16x16x32_bf16 v[34:37], v[194:197], v[164:167], v[34:37]
	v_mfma_f32_16x16x32_bf16 v[30:33], v[194:197], v[186:189], v[30:33]
	v_mfma_f32_16x16x32_bf16 v[26:29], v[202:205], v[164:167], v[26:29]
	v_mfma_f32_16x16x32_bf16 v[22:25], v[202:205], v[186:189], v[22:25]
	v_mfma_f32_16x16x32_bf16 v[18:21], v[210:213], v[164:167], v[18:21]
	v_mfma_f32_16x16x32_bf16 v[14:17], v[210:213], v[186:189], v[14:17]
	v_mfma_f32_16x16x32_bf16 v[10:13], v[218:221], v[164:167], v[10:13]
	v_mfma_f32_16x16x32_bf16 v[6:9], v[218:221], v[186:189], v[6:9]
	v_mfma_f32_16x16x32_bf16 v[34:37], v[198:201], v[182:185], v[34:37]
	v_mfma_f32_16x16x32_bf16 v[30:33], v[198:201], v[190:193], v[30:33]
	v_mfma_f32_16x16x32_bf16 v[26:29], v[206:209], v[182:185], v[26:29]
	v_mfma_f32_16x16x32_bf16 v[22:25], v[206:209], v[190:193], v[22:25]
	v_mfma_f32_16x16x32_bf16 v[18:21], v[214:217], v[182:185], v[18:21]
	v_mfma_f32_16x16x32_bf16 v[14:17], v[214:217], v[190:193], v[14:17]
	v_mfma_f32_16x16x32_bf16 v[10:13], v[222:225], v[182:185], v[10:13]
	v_mfma_f32_16x16x32_bf16 v[6:9], v[222:225], v[190:193], v[6:9]
	s_barrier
	v_readfirstlane_b32 s0, v148
	v_lshl_add_u64 v[164:165], v[246:247], 0, s[24:25]
	s_mov_b32 m0, s0
	v_readfirstlane_b32 s0, v149
	global_load_lds_dwordx4 v[164:165], off
	s_mov_b32 m0, s0
	v_lshl_add_u64 v[164:165], v[248:249], 0, s[24:25]
	global_load_lds_dwordx4 v[164:165], off
	s_waitcnt vmcnt(6)
	s_barrier
	v_mfma_f32_16x16x32_bf16 v[2:5], v[194:197], v[226:229], v[2:5]
	v_mfma_f32_16x16x32_bf16 v[58:61], v[194:197], v[234:237], v[58:61]
	v_mfma_f32_16x16x32_bf16 v[66:69], v[202:205], v[226:229], v[66:69]
	v_mfma_f32_16x16x32_bf16 v[70:73], v[202:205], v[234:237], v[70:73]
	v_mfma_f32_16x16x32_bf16 v[74:77], v[210:213], v[226:229], v[74:77]
	v_mfma_f32_16x16x32_bf16 v[82:85], v[210:213], v[234:237], v[82:85]
	v_mfma_f32_16x16x32_bf16 v[86:89], v[218:221], v[226:229], v[86:89]
	v_mfma_f32_16x16x32_bf16 v[90:93], v[218:221], v[234:237], v[90:93]
	v_mfma_f32_16x16x32_bf16 v[2:5], v[198:201], v[230:233], v[2:5]
	v_mfma_f32_16x16x32_bf16 v[58:61], v[198:201], v[238:241], v[58:61]
	v_mfma_f32_16x16x32_bf16 v[66:69], v[206:209], v[230:233], v[66:69]
	v_mfma_f32_16x16x32_bf16 v[70:73], v[206:209], v[238:241], v[70:73]
	v_mfma_f32_16x16x32_bf16 v[74:77], v[214:217], v[230:233], v[74:77]
	v_mfma_f32_16x16x32_bf16 v[82:85], v[214:217], v[238:241], v[82:85]
	v_mfma_f32_16x16x32_bf16 v[86:89], v[222:225], v[230:233], v[86:89]
	v_mfma_f32_16x16x32_bf16 v[90:93], v[222:225], v[238:241], v[90:93]
	s_barrier
	ds_read_b128 v[164:167], v150
	ds_read_b128 v[182:185], v150 offset:1024
	ds_read_b128 v[186:189], v150 offset:2048
	ds_read_b128 v[190:193], v150 offset:3072
	v_lshl_add_u64 v[226:227], v[242:243], 0, s[86:87]
	s_add_u32 m0, s32, 0x4000
	v_readfirstlane_b32 s0, v152
	ds_read_b128 v[194:197], v142 offset:32768
	ds_read_b128 v[198:201], v142 offset:33792
	ds_read_b128 v[202:205], v142 offset:34816
	ds_read_b128 v[206:209], v142 offset:35840
	ds_read_b128 v[210:213], v142 offset:36864
	ds_read_b128 v[214:217], v142 offset:37888
	ds_read_b128 v[218:221], v142 offset:38912
	ds_read_b128 v[222:225], v142 offset:39936
	global_load_lds_dwordx4 v[226:227], off
	s_mov_b32 m0, s0
	v_lshl_add_u64 v[226:227], v[244:245], 0, s[86:87]
	global_load_lds_dwordx4 v[226:227], off
	s_waitcnt lgkmcnt(8)
	s_barrier
; #define G_LDA(dst, b, h)                                                                                                  \
;   _Pragma("unroll") for (int m = 0; m < 4; ++m) _Pragma("unroll") for (int k = 0; k < 2; ++k)                             \
;       dst[m][k] = *(const bf16x8*)((const char*)G_SA(b, h) + ((wr * 4 + m) * 2 + k) * 1024 + rdo)
; #define G_LDB(dst, b, h)                                                                                                  \
;   _Pragma("unroll") for (int n = 0; n < 2; ++n) _Pragma("unroll") for (int k = 0; k < 2; ++k)                             \
;       dst[n][k] = *(const bf16x8*)((const char*)G_SB(b, h) + ((wc * 2 + n) * 2 + k) * 1024 + rdo)
; #define G_WAIT_V(n) asm volatile("s_waitcnt vmcnt(" #n ")" ::: "memory")
; #define G_WAIT_L(n) asm volatile("s_waitcnt lgkmcnt(" #n ")" ::: "memory")
; #define G_BAR __builtin_amdgcn_s_barrier()
; #define G_SCHED __builtin_amdgcn_sched_barrier(0)
; DI void br_flush(PREF p, f32x4 (&acc)[2][2][4][2], int slot) { br_store(p, acc, slot); zero_acc256(acc); }
;     ...
;     G_WAIT_L(8); G_BAR; G_WAIT_L(0); G_MMA(0, 0, At, B0); G_BAR; G_SCHED;
;     G_LDB(B1, 1, 1); G_STAGE(G_SB(1, 0), B, ob0, ob1, LDB, 0, KB(tt + 3));
;     G_BAR; G_WAIT_L(0); G_MMA(0, 1, At, B1); G_BAR;
;     G_LDA(At, 1, 1); G_STAGE(G_SA(1, 0), A, oa0, oa1, LDA, 0, KA(tt + 3));
;     G_BAR; G_WAIT_L(0); G_MMA(1, 0, At, B0); G_BAR; G_SCHED;
;     G_STAGE(G_SB(1, 1), B, ob0, ob1, LDB, 128, KB(tt + 3));
;     G_WAIT_V(6); G_BAR; G_MMA(1, 1, At, B1); G_BAR;
;     if (MODE && ((tt + 1) & 3) == 3) br_flush(p, acc, (tt + 1) >> 2);
;   }
	s_waitcnt lgkmcnt(0)
	v_mfma_f32_16x16x32_bf16 v[126:129], v[194:197], v[164:167], v[126:129]
	v_mfma_f32_16x16x32_bf16 v[122:125], v[194:197], v[186:189], v[122:125]
	v_mfma_f32_16x16x32_bf16 v[118:121], v[202:205], v[164:167], v[118:121]
	v_mfma_f32_16x16x32_bf16 v[114:117], v[202:205], v[186:189], v[114:117]
	v_mfma_f32_16x16x32_bf16 v[110:113], v[210:213], v[164:167], v[110:113]
	v_mfma_f32_16x16x32_bf16 v[106:109], v[210:213], v[186:189], v[106:109]
	v_mfma_f32_16x16x32_bf16 v[102:105], v[218:221], v[164:167], v[102:105]
	v_mfma_f32_16x16x32_bf16 v[98:101], v[218:221], v[186:189], v[98:101]
	v_mfma_f32_16x16x32_bf16 v[126:129], v[198:201], v[182:185], v[126:129]
	v_mfma_f32_16x16x32_bf16 v[122:125], v[198:201], v[190:193], v[122:125]
	v_mfma_f32_16x16x32_bf16 v[118:121], v[206:209], v[182:185], v[118:121]
	v_mfma_f32_16x16x32_bf16 v[114:117], v[206:209], v[190:193], v[114:117]
	v_mfma_f32_16x16x32_bf16 v[110:113], v[214:217], v[182:185], v[110:113]
	v_mfma_f32_16x16x32_bf16 v[106:109], v[214:217], v[190:193], v[106:109]
	v_mfma_f32_16x16x32_bf16 v[102:105], v[222:225], v[182:185], v[102:105]
	v_mfma_f32_16x16x32_bf16 v[98:101], v[222:225], v[190:193], v[98:101]
	s_barrier
	v_readfirstlane_b32 s0, v153
	v_lshl_add_u64 v[250:251], v[246:247], 0, s[36:37]
	s_mov_b32 m0, s0
	v_readfirstlane_b32 s0, v154
	ds_read_b128 v[226:229], v145
	ds_read_b128 v[230:233], v145 offset:1024
	ds_read_b128 v[234:237], v145 offset:2048
	ds_read_b128 v[238:241], v145 offset:3072
	global_load_lds_dwordx4 v[250:251], off
	s_mov_b32 m0, s0
	v_lshl_add_u64 v[250:251], v[248:249], 0, s[36:37]
	global_load_lds_dwordx4 v[250:251], off
	s_barrier
	s_waitcnt lgkmcnt(0)
	v_mfma_f32_16x16x32_bf16 v[94:97], v[194:197], v[226:229], v[94:97]
	v_mfma_f32_16x16x32_bf16 v[78:81], v[194:197], v[234:237], v[78:81]
	v_mfma_f32_16x16x32_bf16 v[62:65], v[202:205], v[226:229], v[62:65]
	v_mfma_f32_16x16x32_bf16 v[54:57], v[202:205], v[234:237], v[54:57]
	v_mfma_f32_16x16x32_bf16 v[50:53], v[210:213], v[226:229], v[50:53]
	v_mfma_f32_16x16x32_bf16 v[46:49], v[210:213], v[234:237], v[46:49]
	v_mfma_f32_16x16x32_bf16 v[42:45], v[218:221], v[226:229], v[42:45]
	v_mfma_f32_16x16x32_bf16 v[38:41], v[218:221], v[234:237], v[38:41]
	v_mfma_f32_16x16x32_bf16 v[94:97], v[198:201], v[230:233], v[94:97]
	v_mfma_f32_16x16x32_bf16 v[78:81], v[198:201], v[238:241], v[78:81]
	v_mfma_f32_16x16x32_bf16 v[62:65], v[206:209], v[230:233], v[62:65]
	v_mfma_f32_16x16x32_bf16 v[54:57], v[206:209], v[238:241], v[54:57]
	v_mfma_f32_16x16x32_bf16 v[50:53], v[214:217], v[230:233], v[50:53]
	v_mfma_f32_16x16x32_bf16 v[46:49], v[214:217], v[238:241], v[46:49]
	v_mfma_f32_16x16x32_bf16 v[42:45], v[222:225], v[230:233], v[42:45]
	v_mfma_f32_16x16x32_bf16 v[38:41], v[222:225], v[238:241], v[38:41]
	v_readfirstlane_b32 s0, v155
	v_lshl_add_u64 v[242:243], v[242:243], 0, s[90:91]
	s_mov_b32 m0, s0
	s_barrier
	ds_read_b128 v[194:197], v142 offset:49152
	ds_read_b128 v[198:201], v142 offset:50176
	ds_read_b128 v[202:205], v142 offset:51200
	ds_read_b128 v[206:209], v142 offset:52224
	ds_read_b128 v[210:213], v142 offset:53248
	ds_read_b128 v[214:217], v142 offset:54272
	ds_read_b128 v[218:221], v142 offset:55296
	ds_read_b128 v[222:225], v142 offset:56320
	global_load_lds_dwordx4 v[242:243], off
	s_add_u32 m0, s32, 0xa000
	v_lshl_add_u64 v[242:243], v[244:245], 0, s[90:91]
	global_load_lds_dwordx4 v[242:243], off
	s_barrier
	s_waitcnt lgkmcnt(0)
	v_mfma_f32_16x16x32_bf16 v[34:37], v[194:197], v[164:167], v[34:37]
	v_mfma_f32_16x16x32_bf16 v[30:33], v[194:197], v[186:189], v[30:33]
	v_mfma_f32_16x16x32_bf16 v[26:29], v[202:205], v[164:167], v[26:29]
	v_mfma_f32_16x16x32_bf16 v[22:25], v[202:205], v[186:189], v[22:25]
	v_mfma_f32_16x16x32_bf16 v[18:21], v[210:213], v[164:167], v[18:21]
	v_mfma_f32_16x16x32_bf16 v[14:17], v[210:213], v[186:189], v[14:17]
	v_mfma_f32_16x16x32_bf16 v[10:13], v[218:221], v[164:167], v[10:13]
	v_mfma_f32_16x16x32_bf16 v[6:9], v[218:221], v[186:189], v[6:9]
	v_mfma_f32_16x16x32_bf16 v[34:37], v[198:201], v[182:185], v[34:37]
	v_mfma_f32_16x16x32_bf16 v[30:33], v[198:201], v[190:193], v[30:33]
	v_mfma_f32_16x16x32_bf16 v[26:29], v[206:209], v[182:185], v[26:29]
	v_mfma_f32_16x16x32_bf16 v[22:25], v[206:209], v[190:193], v[22:25]
	v_mfma_f32_16x16x32_bf16 v[18:21], v[214:217], v[182:185], v[18:21]
	v_mfma_f32_16x16x32_bf16 v[14:17], v[214:217], v[190:193], v[14:17]
	v_mfma_f32_16x16x32_bf16 v[10:13], v[222:225], v[182:185], v[10:13]
	v_mfma_f32_16x16x32_bf16 v[6:9], v[222:225], v[190:193], v[6:9]
	s_barrier
	v_lshl_add_u64 v[164:165], v[246:247], 0, s[40:41]
	s_add_u32 m0, s32, 0x1c000
	s_nop 0
	global_load_lds_dwordx4 v[164:165], off
	s_add_u32 m0, s32, 0x1e000
	v_lshl_add_u64 v[164:165], v[248:249], 0, s[40:41]
	global_load_lds_dwordx4 v[164:165], off
	s_waitcnt vmcnt(6)
	s_barrier
	v_mfma_f32_16x16x32_bf16 v[2:5], v[194:197], v[226:229], v[2:5]
	v_mfma_f32_16x16x32_bf16 v[58:61], v[194:197], v[234:237], v[58:61]
	v_mfma_f32_16x16x32_bf16 v[66:69], v[202:205], v[226:229], v[66:69]
	v_mfma_f32_16x16x32_bf16 v[70:73], v[202:205], v[234:237], v[70:73]
	v_mfma_f32_16x16x32_bf16 v[74:77], v[210:213], v[226:229], v[74:77]
	v_mfma_f32_16x16x32_bf16 v[82:85], v[210:213], v[234:237], v[82:85]
	v_mfma_f32_16x16x32_bf16 v[86:89], v[218:221], v[226:229], v[86:89]
	v_mfma_f32_16x16x32_bf16 v[90:93], v[218:221], v[234:237], v[90:93]
	v_mfma_f32_16x16x32_bf16 v[2:5], v[198:201], v[230:233], v[2:5]
	v_mfma_f32_16x16x32_bf16 v[58:61], v[198:201], v[238:241], v[58:61]
	v_mfma_f32_16x16x32_bf16 v[66:69], v[206:209], v[230:233], v[66:69]
	v_mfma_f32_16x16x32_bf16 v[70:73], v[206:209], v[238:241], v[70:73]
	v_mfma_f32_16x16x32_bf16 v[74:77], v[214:217], v[230:233], v[74:77]
	v_mfma_f32_16x16x32_bf16 v[82:85], v[214:217], v[238:241], v[82:85]
	v_mfma_f32_16x16x32_bf16 v[86:89], v[222:225], v[230:233], v[86:89]
	v_mfma_f32_16x16x32_bf16 v[90:93], v[222:225], v[238:241], v[90:93]
	s_add_i32 s22, s22, 2
	s_add_u32 s20, s20, 0x100
	s_addc_u32 s21, s21, 0
	s_cmp_lt_u32 s22, 12
	s_barrier
; #define G_LDA(dst, b, h)                                                                                                  \
;   _Pragma("unroll") for (int m = 0; m < 4; ++m) _Pragma("unroll") for (int k = 0; k < 2; ++k)                             \
;       dst[m][k] = *(const bf16x8*)((const char*)G_SA(b, h) + ((wr * 4 + m) * 2 + k) * 1024 + rdo)
; #define G_LDB(dst, b, h)                                                                                                  \
;   _Pragma("unroll") for (int n = 0; n < 2; ++n) _Pragma("unroll") for (int k = 0; k < 2; ++k)                             \
;       dst[n][k] = *(const bf16x8*)((const char*)G_SB(b, h) + ((wc * 2 + n) * 2 + k) * 1024 + rdo)
; #define G_WAIT_V(n) asm volatile("s_waitcnt vmcnt(" #n ")" ::: "memory")
; #define G_WAIT_L(n) asm volatile("s_waitcnt lgkmcnt(" #n ")" ::: "memory")
; #define G_BAR __builtin_amdgcn_s_barrier()
;     ...
;   }
;   {
;     G_LDB(B0, 0, 0); G_LDA(At, 0, 0); G_STAGE(G_SA(1, 1), A, oa0, oa1, LDA, 128, KA(nt - 1));
;     G_BAR; G_WAIT_L(0); G_MMA(0, 0, At, B0); G_BAR;
;     G_LDB(B1, 0, 1); G_BAR; G_WAIT_L(0); G_MMA(0, 1, At, B1); G_BAR;
;     G_LDA(At, 0, 1); G_WAIT_V(4); G_BAR; G_WAIT_L(0); G_MMA(1, 0, At, B0); G_MMA(1, 1, At, B1); G_BAR;
	s_cbranch_scc1 .LBB0_40
	s_add_u32 s0, s16, 0x40780
	s_addc_u32 s1, s17, 0
	v_lshl_add_u64 v[132:133], v[132:133], 1, s[0:1]
	s_add_u32 m0, s32, 0xc000
	v_lshl_add_u64 v[130:131], v[130:131], 1, s[0:1]
	ds_read_b128 v[134:137], v162
	ds_read_b128 v[138:141], v162 offset:1024
	ds_read_b128 v[146:149], v162 offset:2048
	ds_read_b128 v[152:155], v162 offset:3072
	ds_read_b128 v[164:167], v142
	ds_read_b128 v[182:185], v142 offset:1024
	ds_read_b128 v[186:189], v142 offset:2048
	ds_read_b128 v[190:193], v142 offset:3072
	ds_read_b128 v[194:197], v142 offset:4096
	ds_read_b128 v[198:201], v142 offset:5120
	ds_read_b128 v[202:205], v142 offset:6144
	ds_read_b128 v[206:209], v142 offset:7168
	global_load_lds_dwordx4 v[132:133], off
	s_add_u32 m0, s32, 0xe000
	s_nop 0
	global_load_lds_dwordx4 v[130:131], off
	s_barrier
	s_waitcnt lgkmcnt(0)
	v_mfma_f32_16x16x32_bf16 v[126:129], v[164:167], v[134:137], v[126:129]
	v_mfma_f32_16x16x32_bf16 v[122:125], v[164:167], v[146:149], v[122:125]
	v_mfma_f32_16x16x32_bf16 v[110:113], v[194:197], v[134:137], v[110:113]
	v_mfma_f32_16x16x32_bf16 v[102:105], v[202:205], v[134:137], v[102:105]
	v_mfma_f32_16x16x32_bf16 v[126:129], v[182:185], v[138:141], v[126:129]
	v_mfma_f32_16x16x32_bf16 v[122:125], v[182:185], v[152:155], v[122:125]
	v_mfma_f32_16x16x32_bf16 v[118:121], v[186:189], v[134:137], v[118:121]
	v_mfma_f32_16x16x32_bf16 v[114:117], v[186:189], v[146:149], v[114:117]
	v_mfma_f32_16x16x32_bf16 v[110:113], v[198:201], v[138:141], v[110:113]
	v_mfma_f32_16x16x32_bf16 v[106:109], v[194:197], v[146:149], v[106:109]
	v_mfma_f32_16x16x32_bf16 v[102:105], v[206:209], v[138:141], v[102:105]
	v_mfma_f32_16x16x32_bf16 v[98:101], v[202:205], v[146:149], v[98:101]
	v_mfma_f32_16x16x32_bf16 v[130:133], v[190:193], v[138:141], v[118:121]
	v_mfma_f32_16x16x32_bf16 v[210:213], v[190:193], v[152:155], v[114:117]
	v_mfma_f32_16x16x32_bf16 v[214:217], v[198:201], v[152:155], v[106:109]
	v_mfma_f32_16x16x32_bf16 v[218:221], v[206:209], v[152:155], v[98:101]
	s_barrier
	s_nop 1
	s_nop 0
	ds_read_b128 v[98:101], v159
	ds_read_b128 v[106:109], v159 offset:1024
	ds_read_b128 v[114:117], v159 offset:2048
	ds_read_b128 v[118:121], v159 offset:3072
	s_barrier
	s_waitcnt lgkmcnt(0)
	v_mfma_f32_16x16x32_bf16 v[94:97], v[164:167], v[98:101], v[94:97]
	v_mfma_f32_16x16x32_bf16 v[78:81], v[164:167], v[114:117], v[78:81]
	v_mfma_f32_16x16x32_bf16 v[62:65], v[186:189], v[98:101], v[62:65]
	v_mfma_f32_16x16x32_bf16 v[54:57], v[186:189], v[114:117], v[54:57]
	v_mfma_f32_16x16x32_bf16 v[50:53], v[194:197], v[98:101], v[50:53]
	v_mfma_f32_16x16x32_bf16 v[46:49], v[194:197], v[114:117], v[46:49]
	v_mfma_f32_16x16x32_bf16 v[42:45], v[202:205], v[98:101], v[42:45]
	v_mfma_f32_16x16x32_bf16 v[38:41], v[202:205], v[114:117], v[38:41]
	v_mfma_f32_16x16x32_bf16 v[94:97], v[182:185], v[106:109], v[94:97]
	v_mfma_f32_16x16x32_bf16 v[78:81], v[182:185], v[118:121], v[78:81]
	v_mfma_f32_16x16x32_bf16 v[62:65], v[190:193], v[106:109], v[62:65]
	v_mfma_f32_16x16x32_bf16 v[54:57], v[190:193], v[118:121], v[54:57]
	v_mfma_f32_16x16x32_bf16 v[50:53], v[198:201], v[106:109], v[50:53]
	v_mfma_f32_16x16x32_bf16 v[46:49], v[198:201], v[118:121], v[46:49]
	v_mfma_f32_16x16x32_bf16 v[42:45], v[206:209], v[106:109], v[42:45]
	v_mfma_f32_16x16x32_bf16 v[38:41], v[206:209], v[118:121], v[38:41]
	s_barrier
	ds_read_b128 v[156:159], v142 offset:16384
	ds_read_b128 v[164:167], v142 offset:17408
	ds_read_b128 v[182:185], v142 offset:18432
	ds_read_b128 v[186:189], v142 offset:19456
	ds_read_b128 v[190:193], v142 offset:20480
	ds_read_b128 v[194:197], v142 offset:21504
	ds_read_b128 v[198:201], v142 offset:22528
	ds_read_b128 v[202:205], v142 offset:23552
	s_waitcnt vmcnt(4)
	s_barrier
	s_waitcnt lgkmcnt(0)
	v_mfma_f32_16x16x32_bf16 v[34:37], v[156:159], v[134:137], v[34:37]
	v_mfma_f32_16x16x32_bf16 v[30:33], v[156:159], v[146:149], v[30:33]
	v_mfma_f32_16x16x32_bf16 v[26:29], v[182:185], v[134:137], v[26:29]
	v_mfma_f32_16x16x32_bf16 v[22:25], v[182:185], v[146:149], v[22:25]
	v_mfma_f32_16x16x32_bf16 v[18:21], v[190:193], v[134:137], v[18:21]
	v_mfma_f32_16x16x32_bf16 v[14:17], v[190:193], v[146:149], v[14:17]
	v_mfma_f32_16x16x32_bf16 v[10:13], v[198:201], v[134:137], v[10:13]
	v_mfma_f32_16x16x32_bf16 v[6:9], v[198:201], v[146:149], v[6:9]
	v_mfma_f32_16x16x32_bf16 v[34:37], v[164:167], v[138:141], v[34:37]
	v_mfma_f32_16x16x32_bf16 v[30:33], v[164:167], v[152:155], v[30:33]
	v_mfma_f32_16x16x32_bf16 v[26:29], v[186:189], v[138:141], v[26:29]
	v_mfma_f32_16x16x32_bf16 v[22:25], v[186:189], v[152:155], v[22:25]
	v_mfma_f32_16x16x32_bf16 v[18:21], v[194:197], v[138:141], v[18:21]
	v_mfma_f32_16x16x32_bf16 v[14:17], v[194:197], v[152:155], v[14:17]
	v_mfma_f32_16x16x32_bf16 v[10:13], v[202:205], v[138:141], v[10:13]
	v_mfma_f32_16x16x32_bf16 v[6:9], v[202:205], v[152:155], v[6:9]
	v_mfma_f32_16x16x32_bf16 v[58:61], v[156:159], v[114:117], v[58:61]
	v_mfma_f32_16x16x32_bf16 v[134:137], v[164:167], v[118:121], v[58:61]
	v_mfma_f32_16x16x32_bf16 v[58:61], v[182:185], v[98:101], v[66:69]
	v_mfma_f32_16x16x32_bf16 v[138:141], v[186:189], v[106:109], v[58:61]
	v_mfma_f32_16x16x32_bf16 v[58:61], v[182:185], v[114:117], v[70:73]
	v_mfma_f32_16x16x32_bf16 v[146:149], v[186:189], v[118:121], v[58:61]
	v_mfma_f32_16x16x32_bf16 v[58:61], v[190:193], v[98:101], v[74:77]
	v_mfma_f32_16x16x32_bf16 v[152:155], v[194:197], v[106:109], v[58:61]
	v_mfma_f32_16x16x32_bf16 v[58:61], v[190:193], v[114:117], v[82:85]
	v_mfma_f32_16x16x32_bf16 v[2:5], v[156:159], v[98:101], v[2:5]
	v_mfma_f32_16x16x32_bf16 v[156:159], v[194:197], v[118:121], v[58:61]
	v_mfma_f32_16x16x32_bf16 v[58:61], v[198:201], v[98:101], v[86:89]
	v_mfma_f32_16x16x32_bf16 v[2:5], v[164:167], v[106:109], v[2:5]
	v_mfma_f32_16x16x32_bf16 v[164:167], v[202:205], v[106:109], v[58:61]
	v_mfma_f32_16x16x32_bf16 v[58:61], v[198:201], v[114:117], v[90:93]
	v_mfma_f32_16x16x32_bf16 v[182:185], v[202:205], v[118:121], v[58:61]
	s_barrier
; #define G_LDA(dst, b, h)                                                                                                  \
;   _Pragma("unroll") for (int m = 0; m < 4; ++m) _Pragma("unroll") for (int k = 0; k < 2; ++k)                             \
;       dst[m][k] = *(const bf16x8*)((const char*)G_SA(b, h) + ((wr * 4 + m) * 2 + k) * 1024 + rdo)
; #define G_LDB(dst, b, h)                                                                                                  \
;   _Pragma("unroll") for (int n = 0; n < 2; ++n) _Pragma("unroll") for (int k = 0; k < 2; ++k)                             \
;       dst[n][k] = *(const bf16x8*)((const char*)G_SB(b, h) + ((wc * 2 + n) * 2 + k) * 1024 + rdo)
; #define G_WAIT_V(n) asm volatile("s_waitcnt vmcnt(" #n ")" ::: "memory")
; #define G_WAIT_L(n) asm volatile("s_waitcnt lgkmcnt(" #n ")" ::: "memory")
; #define G_BAR __builtin_amdgcn_s_barrier()
;     ...
;     G_LDA(At, 0, 1); G_WAIT_V(4); G_BAR; G_WAIT_L(0); G_MMA(1, 0, At, B0); G_MMA(1, 1, At, B1); G_BAR;
;   }
;   {
;     G_LDB(B0, 1, 0); G_LDA(At, 1, 0); G_WAIT_V(2); G_BAR; G_WAIT_L(0); G_MMA(0, 0, At, B0); G_BAR;
;     G_LDB(B1, 1, 1); G_WAIT_V(0); G_BAR; G_WAIT_L(0); G_MMA(0, 1, At, B1); G_BAR;
;     G_LDA(At, 1, 1); G_BAR; G_WAIT_L(0); G_MMA(1, 0, At, B0); G_MMA(1, 1, At, B1); G_BAR;
;   }
;   if (wr == 0) G_BAR;
	ds_read_b128 v[186:189], v150
	ds_read_b128 v[190:193], v150 offset:1024
	ds_read_b128 v[194:197], v150 offset:2048
	ds_read_b128 v[198:201], v150 offset:3072
	s_nop 0
	s_nop 0
	ds_read_b128 v[58:61], v142 offset:32768
	ds_read_b128 v[66:69], v142 offset:33792
	ds_read_b128 v[70:73], v142 offset:34816
	ds_read_b128 v[74:77], v142 offset:35840
	ds_read_b128 v[202:205], v142 offset:36864
	ds_read_b128 v[206:209], v142 offset:37888
	ds_read_b128 v[222:225], v142 offset:38912
	ds_read_b128 v[226:229], v142 offset:39936
	s_waitcnt vmcnt(2)
	s_barrier
	s_waitcnt lgkmcnt(0)
	v_mfma_f32_16x16x32_bf16 v[82:85], v[58:61], v[186:189], v[126:129]
	v_mfma_f32_16x16x32_bf16 v[118:121], v[66:69], v[190:193], v[82:85]
	v_mfma_f32_16x16x32_bf16 v[82:85], v[58:61], v[194:197], v[122:125]
	v_mfma_f32_16x16x32_bf16 v[126:129], v[66:69], v[198:201], v[82:85]
	v_mfma_f32_16x16x32_bf16 v[82:85], v[70:73], v[186:189], v[130:133]
	v_mfma_f32_16x16x32_bf16 v[114:117], v[74:77], v[190:193], v[82:85]
	v_mfma_f32_16x16x32_bf16 v[82:85], v[70:73], v[194:197], v[210:213]
	v_mfma_f32_16x16x32_bf16 v[122:125], v[74:77], v[198:201], v[82:85]
	v_mfma_f32_16x16x32_bf16 v[82:85], v[202:205], v[186:189], v[110:113]
	v_mfma_f32_16x16x32_bf16 v[106:109], v[206:209], v[190:193], v[82:85]
	v_mfma_f32_16x16x32_bf16 v[82:85], v[202:205], v[194:197], v[214:217]
	v_mfma_f32_16x16x32_bf16 v[110:113], v[206:209], v[198:201], v[82:85]
	v_mfma_f32_16x16x32_bf16 v[82:85], v[222:225], v[186:189], v[102:105]
	v_mfma_f32_16x16x32_bf16 v[98:101], v[226:229], v[190:193], v[82:85]
	v_mfma_f32_16x16x32_bf16 v[82:85], v[222:225], v[194:197], v[218:221]
	v_mfma_f32_16x16x32_bf16 v[102:105], v[226:229], v[198:201], v[82:85]
	s_barrier
	ds_read_b128 v[130:133], v145
	ds_read_b128 v[210:213], v145 offset:1024
	ds_read_b128 v[214:217], v145 offset:2048
	ds_read_b128 v[218:221], v145 offset:3072
	s_waitcnt vmcnt(0)
	s_barrier
	s_waitcnt lgkmcnt(0)
	v_mfma_f32_16x16x32_bf16 v[82:85], v[58:61], v[130:133], v[94:97]
	v_mfma_f32_16x16x32_bf16 v[58:61], v[58:61], v[214:217], v[78:81]
	v_mfma_f32_16x16x32_bf16 v[94:97], v[66:69], v[218:221], v[58:61]
	v_mfma_f32_16x16x32_bf16 v[58:61], v[70:73], v[130:133], v[62:65]
	v_mfma_f32_16x16x32_bf16 v[54:57], v[70:73], v[214:217], v[54:57]
	v_mfma_f32_16x16x32_bf16 v[50:53], v[202:205], v[130:133], v[50:53]
	v_mfma_f32_16x16x32_bf16 v[46:49], v[202:205], v[214:217], v[46:49]
	v_mfma_f32_16x16x32_bf16 v[42:45], v[222:225], v[130:133], v[42:45]
	v_mfma_f32_16x16x32_bf16 v[38:41], v[222:225], v[214:217], v[38:41]
	v_mfma_f32_16x16x32_bf16 v[86:89], v[66:69], v[210:213], v[82:85]
	v_mfma_f32_16x16x32_bf16 v[82:85], v[74:77], v[210:213], v[58:61]
	v_mfma_f32_16x16x32_bf16 v[90:93], v[74:77], v[218:221], v[54:57]
	v_mfma_f32_16x16x32_bf16 v[74:77], v[206:209], v[210:213], v[50:53]
	v_mfma_f32_16x16x32_bf16 v[78:81], v[206:209], v[218:221], v[46:49]
	v_mfma_f32_16x16x32_bf16 v[66:69], v[226:229], v[210:213], v[42:45]
	v_mfma_f32_16x16x32_bf16 v[70:73], v[226:229], v[218:221], v[38:41]
	s_barrier
	ds_read_b128 v[202:205], v142 offset:49152
	ds_read_b128 v[206:209], v142 offset:50176
	ds_read_b128 v[222:225], v142 offset:51200
	ds_read_b128 v[226:229], v142 offset:52224
	ds_read_b128 v[230:233], v142 offset:53248
	ds_read_b128 v[234:237], v142 offset:54272
	ds_read_b128 v[238:241], v142 offset:55296
	ds_read_b128 v[142:145], v142 offset:56320
	s_barrier
	s_waitcnt lgkmcnt(0)
	v_mfma_f32_16x16x32_bf16 v[34:37], v[202:205], v[186:189], v[34:37]
	v_mfma_f32_16x16x32_bf16 v[30:33], v[202:205], v[194:197], v[30:33]
	v_mfma_f32_16x16x32_bf16 v[26:29], v[222:225], v[186:189], v[26:29]
	v_mfma_f32_16x16x32_bf16 v[22:25], v[222:225], v[194:197], v[22:25]
	v_mfma_f32_16x16x32_bf16 v[18:21], v[230:233], v[186:189], v[18:21]
	v_mfma_f32_16x16x32_bf16 v[14:17], v[230:233], v[194:197], v[14:17]
	v_mfma_f32_16x16x32_bf16 v[10:13], v[238:241], v[186:189], v[10:13]
	v_mfma_f32_16x16x32_bf16 v[6:9], v[238:241], v[194:197], v[6:9]
	v_mfma_f32_16x16x32_bf16 v[54:57], v[206:209], v[190:193], v[34:37]
	v_mfma_f32_16x16x32_bf16 v[62:65], v[206:209], v[198:201], v[30:33]
	v_mfma_f32_16x16x32_bf16 v[50:53], v[226:229], v[190:193], v[26:29]
	v_mfma_f32_16x16x32_bf16 v[58:61], v[226:229], v[198:201], v[22:25]
	v_mfma_f32_16x16x32_bf16 v[42:45], v[234:237], v[190:193], v[18:21]
	v_mfma_f32_16x16x32_bf16 v[46:49], v[234:237], v[198:201], v[14:17]
	v_mfma_f32_16x16x32_bf16 v[34:37], v[142:145], v[190:193], v[10:13]
	v_mfma_f32_16x16x32_bf16 v[38:41], v[142:145], v[198:201], v[6:9]
	v_mfma_f32_16x16x32_bf16 v[2:5], v[202:205], v[130:133], v[2:5]
	v_mfma_f32_16x16x32_bf16 v[22:25], v[206:209], v[210:213], v[2:5]
	v_mfma_f32_16x16x32_bf16 v[2:5], v[202:205], v[214:217], v[134:137]
	v_mfma_f32_16x16x32_bf16 v[30:33], v[206:209], v[218:221], v[2:5]
	v_mfma_f32_16x16x32_bf16 v[2:5], v[222:225], v[130:133], v[138:141]
	v_mfma_f32_16x16x32_bf16 v[18:21], v[226:229], v[210:213], v[2:5]
	v_mfma_f32_16x16x32_bf16 v[2:5], v[222:225], v[214:217], v[146:149]
	v_mfma_f32_16x16x32_bf16 v[26:29], v[226:229], v[218:221], v[2:5]
	v_mfma_f32_16x16x32_bf16 v[2:5], v[230:233], v[130:133], v[152:155]
	v_mfma_f32_16x16x32_bf16 v[10:13], v[234:237], v[210:213], v[2:5]
	v_mfma_f32_16x16x32_bf16 v[2:5], v[230:233], v[214:217], v[156:159]
	v_mfma_f32_16x16x32_bf16 v[14:17], v[234:237], v[218:221], v[2:5]
	v_mfma_f32_16x16x32_bf16 v[2:5], v[238:241], v[130:133], v[164:167]
	v_mfma_f32_16x16x32_bf16 v[6:9], v[238:241], v[214:217], v[182:185]
	v_mfma_f32_16x16x32_bf16 v[2:5], v[142:145], v[210:213], v[2:5]
	v_mfma_f32_16x16x32_bf16 v[6:9], v[142:145], v[218:221], v[6:9]
	v_cmp_gt_u32_e32 vcc, s67, v0
	s_barrier
	s_and_saveexec_b64 s[16:17], vcc
	s_cbranch_execz .LBB0_43
	s_barrier

; DI void lds_barrier() { asm volatile("s_waitcnt lgkmcnt(0)\n\ts_barrier" ::: "memory"); }
; DI int tid512() { int t = threadIdx.x; asm volatile("" : "+v"(t)); return t; }
; #define G_WAIT_V(n) asm volatile("s_waitcnt vmcnt(" #n ")" ::: "memory")
; #define G_BAR __builtin_amdgcn_s_barrier()
;     ...
;   const int t = tid512();
;   const int wid = t >> 6, lane = t & 63, wr = wid >> 2, wc = wid & 3, fr = lane & 15, fq = lane >> 4;
;   int r0, c0, r1, c1;
;   g_stage_rc(t * 16, r0, c0); g_stage_rc(t * 16 + 8192, r1, c1);
;   const int oa0 = r0 * LDA + c0, oa1 = r1 * LDA + c1, ob0 = r0 * LDB + c0, ob1 = r1 * LDB + c1;
;   const int obr = fr * 64 + fq * 16, rdo = obr ^ (((obr >> 9) & 1) << 5);
;   bf16x8 At[4][2], B0[2][2], B1[2][2];
;   constexpr int nt = K / 64;
;   lds_barrier();
;   G_STAGE(G_SB(0, 0), B, ob0, ob1, LDB, 0, KB(0)); G_STAGE(G_SA(0, 0), A, oa0, oa1, LDA, 0, KA(0));
;   G_STAGE(G_SB(0, 1), B, ob0, ob1, LDB, 128, KB(0)); G_STAGE(G_SA(0, 1), A, oa0, oa1, LDA, 128, KA(0));
;   if (wr == 1) G_BAR;
;   G_WAIT_V(4); G_BAR;
;   G_STAGE(G_SB(1, 0), B, ob0, ob1, LDB, 0, KB(1)); G_STAGE(G_SA(1, 0), A, oa0, oa1, LDA, 0, KA(1)); G_STAGE(G_SB(1, 1), B, ob0, ob1, LDB, 128, KB(1));
;   G_WAIT_V(6); G_BAR;
; DI bool xcd_tile256(int k, int NT, int& m, int& n) {
;   const int x = blockIdx.x & 7, slots = gridDim.x >> 3;
;   const int idx = (int)(blockIdx.x >> 3) + slots * k;
;   if (idx >= 16 * NT) return false;
;   const int mg = idx / (8 * NT), rem = idx - mg * 8 * NT;
;   n = rem >> 3; m = x * 16 + mg * 8 + (rem & 7);
;   return true;
; }
.LBB0_63:
	s_lshr_b32 s0, s9, 2
	s_and_b32 s36, s0, 8
	s_lshl_b32 s0, s36, 2
	s_sub_i32 s0, s9, s0
	s_and_b32 s37, s9, 7
	s_ashr_i32 s8, s0, 3
	s_or_b32 s0, s37, s47
	v_mov_b32_e32 v0, v168
	s_or_b32 s35, s0, s36
	s_lshl_b32 s0, s35, 19
	v_lshlrev_b32_e32 v143, 4, v0
	s_nop 0
	v_readfirstlane_b32 s32, v143
	v_and_b32_e32 v2, 32, v0
	v_lshrrev_b32_e32 v4, 1, v0
	v_bitop3_b32 v2, v143, v2, 48 bitop3:0x6c
	s_add_u32 s20, s10, s0
	v_ashrrev_i32_e32 v10, 3, v0
	v_bfe_u32 v13, v0, 2, 4
	s_mov_b32 s0, 0x3ffff0
	v_and_b32_e32 v11, 32, v4
	v_lshrrev_b32_e32 v12, 1, v2
	v_add_u32_e32 v144, 0x2000, v143
	s_addc_u32 s21, s11, 0
	s_ashr_i32 s9, s8, 31
	v_and_or_b32 v3, v10, s0, v13
	v_or_b32_e32 v2, v12, v11
	v_ashrrev_i32_e32 v15, 7, v144
	s_lshl_b64 s[22:23], s[8:9], 19
	v_and_or_b32 v4, v15, s0, v13
	v_lshl_or_b32 v132, v3, 10, v2
	s_add_u32 s24, s30, s22
	v_lshl_or_b32 v130, v4, 10, v2
	v_ashrrev_i32_e32 v133, 31, v132
	s_addc_u32 s25, s31, s23
	v_lshlrev_b64 v[16:17], 1, v[132:133]
	v_ashrrev_i32_e32 v131, 31, v130
	s_waitcnt lgkmcnt(0)
	s_barrier
	v_lshl_add_u64 v[2:3], s[24:25], 0, v[16:17]
	s_add_u32 m0, s32, 0x10000
	v_lshlrev_b64 v[18:19], 1, v[130:131]
	global_load_lds_dwordx4 v[2:3], off
	v_lshl_add_u64 v[6:7], s[24:25], 0, v[18:19]
	s_add_u32 m0, s32, 0x12000
	s_nop 0
	global_load_lds_dwordx4 v[6:7], off
	v_lshl_add_u64 v[8:9], s[20:21], 0, v[16:17]
	s_mov_b32 m0, s32
	s_nop 0
	global_load_lds_dwordx4 v[8:9], off
	s_add_u32 m0, s32, 0x2000
	s_add_u32 s0, s24, 0x40000
	v_lshl_add_u64 v[4:5], s[20:21], 0, v[18:19]
	s_addc_u32 s1, s25, 0
	global_load_lds_dwordx4 v[4:5], off
	v_lshl_add_u64 v[20:21], s[0:1], 0, v[16:17]
	s_add_u32 m0, s32, 0x14000
	v_add_u32_e32 v150, 0x16000, v143
	global_load_lds_dwordx4 v[20:21], off
	v_lshl_add_u64 v[20:21], s[0:1], 0, v[18:19]
	v_readfirstlane_b32 s0, v150
	s_mov_b32 m0, s0
	s_add_u32 s0, s20, 0x40000
	v_add_u32_e32 v151, 0x4000, v143
	s_addc_u32 s1, s21, 0
	v_readfirstlane_b32 s9, v151
	global_load_lds_dwordx4 v[20:21], off
	v_lshl_add_u64 v[16:17], s[0:1], 0, v[16:17]
	s_mov_b32 m0, s9
	v_add_u32_e32 v152, 0x6000, v143
	global_load_lds_dwordx4 v[16:17], off
	v_lshl_add_u64 v[16:17], s[0:1], 0, v[18:19]
	v_readfirstlane_b32 s0, v152
	s_mov_b32 m0, s0
	v_ashrrev_i32_e32 v14, 8, v0
	global_load_lds_dwordx4 v[16:17], off
	v_cmp_eq_u32_e32 vcc, 1, v14
	s_and_saveexec_b64 s[26:27], vcc
	s_cbranch_execz .LBB0_65
	s_barrier
.LBB0_65:
	s_or_b64 exec, exec, s[26:27]
	v_add_u32_e32 v153, 0x18000, v143
	v_add_u32_e32 v154, 0x1a000, v143
	v_readfirstlane_b32 s0, v153
	v_lshl_add_u64 v[2:3], v[2:3], 0, s[76:77]
	s_mov_b32 m0, s0
	v_readfirstlane_b32 s0, v154
	v_add_u32_e32 v155, 0x8000, v143
	s_waitcnt vmcnt(4)
	s_barrier
	global_load_lds_dwordx4 v[2:3], off
	v_lshl_add_u64 v[2:3], v[6:7], 0, s[76:77]
	s_mov_b32 m0, s0
	v_readfirstlane_b32 s0, v155
	v_add_u32_e32 v156, 0xa000, v143
	global_load_lds_dwordx4 v[2:3], off
	v_lshl_add_u64 v[2:3], v[8:9], 0, s[76:77]
	s_mov_b32 m0, s0
	v_readfirstlane_b32 s0, v156
	global_load_lds_dwordx4 v[2:3], off
	s_mov_b32 m0, s0
	s_add_u32 s0, s24, 0x40080
	v_add_u32_e32 v157, 0x1c000, v143
	v_lshl_add_u64 v[2:3], v[4:5], 0, s[76:77]
	s_addc_u32 s1, s25, 0
	v_readfirstlane_b32 s9, v157
	global_load_lds_dwordx4 v[2:3], off
	v_lshl_add_u64 v[2:3], v[132:133], 1, s[0:1]
	s_mov_b32 m0, s9
	s_nop 0
	global_load_lds_dwordx4 v[2:3], off
	v_lshl_add_u64 v[2:3], v[130:131], 1, s[0:1]
	s_add_u32 m0, s32, 0x1e000
	v_lshlrev_b32_e32 v17, 6, v0
	global_load_lds_dwordx4 v[2:3], off
	v_and_b32_e32 v16, 48, v0
	v_and_b32_e32 v18, 0x3c0, v17
	v_lshlrev_b32_e32 v20, 2, v0
	v_or_b32_e32 v19, v18, v16
	v_and_b32_e32 v20, 32, v20
	s_mov_b32 s0, 0x14000
	v_bitop3_b32 v8, v19, s0, v20 bitop3:0xde
	s_mov_b32 s0, 0x18000
	v_bitop3_b32 v9, v19, s0, v20 bitop3:0xde
	s_mov_b32 s0, 0x1c000
	v_lshlrev_b32_e32 v2, 10, v15
	v_lshlrev_b32_e32 v5, 10, v10
	v_lshlrev_b32_e32 v7, 13, v14
	v_bitop3_b32 v14, v19, s0, v20 bitop3:0xde
	s_add_i32 s0, s47, s36
	v_and_b32_e32 v2, 0xffffc000, v2
	v_lshlrev_b32_e32 v4, 10, v13
	v_and_b32_e32 v5, 0xffffc000, v5
	s_add_i32 s0, s0, s37
	v_or3_b32 v2, v12, v2, v4
	v_or3_b32 v4, v12, v5, v4
	s_lshl_b32 s0, s0, 19
	v_add_u32_e32 v2, v2, v11
	v_add_u32_e32 v4, v4, v11
	v_ashrrev_i32_e32 v3, 31, v2
	s_add_u32 s0, s10, s0
	v_ashrrev_i32_e32 v5, 31, v4
	v_lshlrev_b64 v[2:3], 1, v[2:3]
	s_addc_u32 s1, s11, 0
	v_lshlrev_b64 v[4:5], 1, v[4:5]
	v_lshl_add_u64 v[134:135], s[0:1], 0, v[2:3]
	v_lshl_add_u64 v[136:137], s[0:1], 0, v[4:5]
	s_add_u32 s0, s28, s22
	s_waitcnt vmcnt(6)
; #define G_LDA(dst, b, h)                                                                                                  \
;   _Pragma("unroll") for (int m = 0; m < 4; ++m) _Pragma("unroll") for (int k = 0; k < 2; ++k)                             \
;       dst[m][k] = *(const bf16x8*)((const char*)G_SA(b, h) + ((wr * 4 + m) * 2 + k) * 1024 + rdo)
; #define G_LDB(dst, b, h)                                                                                                  \
;   _Pragma("unroll") for (int n = 0; n < 2; ++n) _Pragma("unroll") for (int k = 0; k < 2; ++k)                             \
;       dst[n][k] = *(const bf16x8*)((const char*)G_SB(b, h) + ((wc * 2 + n) * 2 + k) * 1024 + rdo)
; #define G_WAIT_L(n) asm volatile("s_waitcnt lgkmcnt(" #n ")" ::: "memory")
; #define G_BAR __builtin_amdgcn_s_barrier()
; #define G_SCHED __builtin_amdgcn_sched_barrier(0)
;     ...
;   for (int tt = 0; tt < nt - 2; tt += 2) {
;     G_LDB(B0, 0, 0); G_SCHED; G_LDA(At, 0, 0); G_STAGE(G_SA(1, 1), A, oa0, oa1, LDA, 128, KA(tt + 1));
;     G_WAIT_L(8); G_BAR; G_WAIT_L(0); G_MMA(0, 0, At, B0); G_BAR; G_SCHED;
; DI void zero_acc256(f32x4 (&a)[2][2][4][2]) {
; #pragma unroll
;   for (int i = 0; i < 2; ++i)
; #pragma unroll
;     for (int j = 0; j < 2; ++j)
; #pragma unroll
;       for (int m = 0; m < 4; ++m)
; #pragma unroll
;         for (int n = 0; n < 2; ++n)
; #pragma unroll
;           for (int e = 0; e < 4; ++e) a[i][j][m][n][e] = 0.f;
; }
	s_addc_u32 s1, s29, s23
	v_bitop3_b32 v16, v18, v20, v16 bitop3:0x36
	v_bitop3_b32 v6, v19, s88, v20 bitop3:0xde
	v_and_b32_e32 v17, 0x3000, v17
	v_lshl_add_u64 v[138:139], s[0:1], 0, v[2:3]
	v_mov_b32_e32 v2, 0
	v_lshl_add_u64 v[140:141], s[0:1], 0, v[4:5]
	s_mov_b32 s9, -2
	s_mov_b64 s[22:23], 0
	v_add_u32_e32 v160, v6, v17
	v_add_u32_e32 v142, v16, v7
	v_add_u32_e32 v158, v8, v17
	v_add_u32_e32 v149, v9, v17
	v_add_u32_e32 v145, v14, v17
	v_mov_b32_e32 v3, v2
	v_mov_b32_e32 v4, v2
	v_mov_b32_e32 v5, v2
	v_mov_b32_e32 v6, v2
	v_mov_b32_e32 v7, v2
	v_mov_b32_e32 v8, v2
	v_mov_b32_e32 v9, v2
	v_mov_b32_e32 v10, v2
	v_mov_b32_e32 v11, v2
	v_mov_b32_e32 v12, v2
	v_mov_b32_e32 v13, v2
	v_mov_b32_e32 v14, v2
	v_mov_b32_e32 v15, v2
	v_mov_b32_e32 v16, v2
	v_mov_b32_e32 v17, v2
	v_mov_b32_e32 v18, v2
	v_mov_b32_e32 v19, v2
	v_mov_b32_e32 v20, v2
	v_mov_b32_e32 v21, v2
	v_mov_b32_e32 v22, v2
	v_mov_b32_e32 v23, v2
	v_mov_b32_e32 v24, v2
	v_mov_b32_e32 v25, v2
	v_mov_b32_e32 v26, v2
	v_mov_b32_e32 v27, v2
	v_mov_b32_e32 v28, v2
	v_mov_b32_e32 v29, v2
	v_mov_b32_e32 v30, v2
	v_mov_b32_e32 v31, v2
	v_mov_b32_e32 v32, v2
	v_mov_b32_e32 v33, v2
	v_mov_b32_e32 v34, v2
	v_mov_b32_e32 v35, v2
	v_mov_b32_e32 v36, v2
	v_mov_b32_e32 v37, v2
	v_mov_b32_e32 v38, v2
	v_mov_b32_e32 v39, v2
	v_mov_b32_e32 v40, v2
	v_mov_b32_e32 v41, v2
	v_mov_b32_e32 v42, v2
	v_mov_b32_e32 v43, v2
	v_mov_b32_e32 v44, v2
	v_mov_b32_e32 v45, v2
	v_mov_b32_e32 v46, v2
	v_mov_b32_e32 v47, v2
	v_mov_b32_e32 v48, v2
	v_mov_b32_e32 v49, v2
	v_mov_b32_e32 v50, v2
	v_mov_b32_e32 v51, v2
	v_mov_b32_e32 v52, v2
	v_mov_b32_e32 v53, v2
	v_mov_b32_e32 v54, v2
	v_mov_b32_e32 v55, v2
	v_mov_b32_e32 v56, v2
	v_mov_b32_e32 v57, v2
	v_mov_b32_e32 v58, v2
	v_mov_b32_e32 v59, v2
	v_mov_b32_e32 v60, v2
	v_mov_b32_e32 v61, v2
	v_mov_b32_e32 v62, v2
	v_mov_b32_e32 v63, v2
	v_mov_b32_e32 v64, v2
	v_mov_b32_e32 v65, v2
	v_mov_b32_e32 v66, v2
	v_mov_b32_e32 v67, v2
	v_mov_b32_e32 v68, v2
	v_mov_b32_e32 v69, v2
	v_mov_b32_e32 v70, v2
	v_mov_b32_e32 v71, v2
	v_mov_b32_e32 v72, v2
	v_mov_b32_e32 v73, v2
	v_mov_b32_e32 v74, v2
	v_mov_b32_e32 v75, v2
	v_mov_b32_e32 v76, v2
	v_mov_b32_e32 v77, v2
	v_mov_b32_e32 v78, v2
	v_mov_b32_e32 v79, v2
	v_mov_b32_e32 v80, v2
	v_mov_b32_e32 v81, v2
	v_mov_b32_e32 v82, v2
	v_mov_b32_e32 v83, v2
	v_mov_b32_e32 v84, v2
	v_mov_b32_e32 v85, v2
	v_mov_b32_e32 v86, v2
	v_mov_b32_e32 v87, v2
	v_mov_b32_e32 v88, v2
	v_mov_b32_e32 v89, v2
	v_mov_b32_e32 v90, v2
	v_mov_b32_e32 v91, v2
	v_mov_b32_e32 v92, v2
	v_mov_b32_e32 v93, v2
	v_mov_b32_e32 v94, v2
	v_mov_b32_e32 v95, v2
	v_mov_b32_e32 v96, v2
	v_mov_b32_e32 v97, v2
	v_mov_b32_e32 v98, v2
	v_mov_b32_e32 v99, v2
	v_mov_b32_e32 v100, v2
	v_mov_b32_e32 v101, v2
	v_mov_b32_e32 v102, v2
	v_mov_b32_e32 v103, v2
	v_mov_b32_e32 v104, v2
	v_mov_b32_e32 v105, v2
	v_mov_b32_e32 v106, v2
	v_mov_b32_e32 v107, v2
	v_mov_b32_e32 v108, v2
	v_mov_b32_e32 v109, v2
	v_mov_b32_e32 v110, v2
	v_mov_b32_e32 v111, v2
	v_mov_b32_e32 v112, v2
	v_mov_b32_e32 v113, v2
	v_mov_b32_e32 v114, v2
	v_mov_b32_e32 v115, v2
	v_mov_b32_e32 v116, v2
	v_mov_b32_e32 v117, v2
	v_mov_b32_e32 v118, v2
	v_mov_b32_e32 v119, v2
	v_mov_b32_e32 v120, v2
	v_mov_b32_e32 v121, v2
	v_mov_b32_e32 v122, v2
	v_mov_b32_e32 v123, v2
	v_mov_b32_e32 v124, v2
	v_mov_b32_e32 v125, v2
	v_mov_b32_e32 v126, v2
	v_mov_b32_e32 v127, v2
	v_mov_b32_e32 v128, v2
	v_mov_b32_e32 v129, v2
	s_mov_b64 s[24:25], 0x1070100
	s_mov_b64 s[26:27], 0x1030180
	s_mov_b64 s[36:37], 0x1070180
	s_barrier
.LBB0_66:
	ds_read_b128 v[164:167], v160
	ds_read_b128 v[182:185], v160 offset:1024
	ds_read_b128 v[186:189], v160 offset:2048
	ds_read_b128 v[190:193], v160 offset:3072
	v_lshl_add_u64 v[242:243], v[136:137], 0, s[22:23]
	v_lshl_add_u64 v[226:227], v[242:243], 0, s[78:79]
	s_add_u32 m0, s32, 0xc000
	v_lshl_add_u64 v[244:245], v[134:135], 0, s[22:23]
	ds_read_b128 v[194:197], v142
	ds_read_b128 v[198:201], v142 offset:1024
	ds_read_b128 v[202:205], v142 offset:2048
	ds_read_b128 v[206:209], v142 offset:3072
	ds_read_b128 v[210:213], v142 offset:4096
	ds_read_b128 v[214:217], v142 offset:5120
	ds_read_b128 v[218:221], v142 offset:6144
	ds_read_b128 v[222:225], v142 offset:7168
	global_load_lds_dwordx4 v[226:227], off
	s_add_u32 m0, s32, 0xe000
	v_lshl_add_u64 v[226:227], v[244:245], 0, s[78:79]
	global_load_lds_dwordx4 v[226:227], off
	s_waitcnt lgkmcnt(8)
	s_barrier
	s_waitcnt lgkmcnt(0)
	v_mfma_f32_16x16x32_bf16 v[126:129], v[194:197], v[164:167], v[126:129]
	v_mfma_f32_16x16x32_bf16 v[122:125], v[194:197], v[186:189], v[122:125]
	v_mfma_f32_16x16x32_bf16 v[118:121], v[202:205], v[164:167], v[118:121]
	v_mfma_f32_16x16x32_bf16 v[114:117], v[202:205], v[186:189], v[114:117]
	v_mfma_f32_16x16x32_bf16 v[110:113], v[210:213], v[164:167], v[110:113]
	v_mfma_f32_16x16x32_bf16 v[106:109], v[210:213], v[186:189], v[106:109]
	v_mfma_f32_16x16x32_bf16 v[102:105], v[218:221], v[164:167], v[102:105]
	v_mfma_f32_16x16x32_bf16 v[98:101], v[218:221], v[186:189], v[98:101]
	v_mfma_f32_16x16x32_bf16 v[126:129], v[198:201], v[182:185], v[126:129]
	v_mfma_f32_16x16x32_bf16 v[122:125], v[198:201], v[190:193], v[122:125]
	v_mfma_f32_16x16x32_bf16 v[118:121], v[206:209], v[182:185], v[118:121]
	v_mfma_f32_16x16x32_bf16 v[114:117], v[206:209], v[190:193], v[114:117]
	v_mfma_f32_16x16x32_bf16 v[110:113], v[214:217], v[182:185], v[110:113]
	v_mfma_f32_16x16x32_bf16 v[106:109], v[214:217], v[190:193], v[106:109]
	v_mfma_f32_16x16x32_bf16 v[102:105], v[222:225], v[182:185], v[102:105]
	v_mfma_f32_16x16x32_bf16 v[98:101], v[222:225], v[190:193], v[98:101]
	s_barrier
; #define G_LDA(dst, b, h)                                                                                                  \
;   _Pragma("unroll") for (int m = 0; m < 4; ++m) _Pragma("unroll") for (int k = 0; k < 2; ++k)                             \
;       dst[m][k] = *(const bf16x8*)((const char*)G_SA(b, h) + ((wr * 4 + m) * 2 + k) * 1024 + rdo)
; #define G_LDB(dst, b, h)                                                                                                  \
;   _Pragma("unroll") for (int n = 0; n < 2; ++n) _Pragma("unroll") for (int k = 0; k < 2; ++k)                             \
;       dst[n][k] = *(const bf16x8*)((const char*)G_SB(b, h) + ((wc * 2 + n) * 2 + k) * 1024 + rdo)
; #define G_WAIT_V(n) asm volatile("s_waitcnt vmcnt(" #n ")" ::: "memory")
; #define G_WAIT_L(n) asm volatile("s_waitcnt lgkmcnt(" #n ")" ::: "memory")
; #define G_BAR __builtin_amdgcn_s_barrier()
; #define G_SCHED __builtin_amdgcn_sched_barrier(0)
;     ...
;     G_WAIT_L(8); G_BAR; G_WAIT_L(0); G_MMA(0, 0, At, B0); G_BAR; G_SCHED;
;     G_LDB(B1, 0, 1); G_STAGE(G_SB(0, 0), B, ob0, ob1, LDB, 0, KB(tt + 2));
;     G_BAR; G_WAIT_L(0); G_MMA(0, 1, At, B1); G_BAR;
;     G_LDA(At, 0, 1); G_STAGE(G_SA(0, 0), A, oa0, oa1, LDA, 0, KA(tt + 2));
;     G_BAR; G_WAIT_L(0); G_MMA(1, 0, At, B0); G_BAR; G_SCHED;
;     G_STAGE(G_SB(0, 1), B, ob0, ob1, LDB, 128, KB(tt + 2));
;     G_WAIT_V(6); G_BAR; G_MMA(1, 1, At, B1); G_BAR;
;     G_LDB(B0, 1, 0); G_SCHED; G_LDA(At, 1, 0); G_STAGE(G_SA(0, 1), A, oa0, oa1, LDA, 128, KA(tt + 2));
;     G_WAIT_L(8); G_BAR; G_WAIT_L(0); G_MMA(0, 0, At, B0); G_BAR; G_SCHED;
	v_lshl_add_u64 v[246:247], v[140:141], 0, s[22:23]
	v_lshl_add_u64 v[248:249], v[246:247], 0, s[48:49]
	s_add_u32 m0, s32, 0x10000
	ds_read_b128 v[226:229], v158
	ds_read_b128 v[230:233], v158 offset:1024
	ds_read_b128 v[234:237], v158 offset:2048
	ds_read_b128 v[238:241], v158 offset:3072
	global_load_lds_dwordx4 v[248:249], off
	v_lshl_add_u64 v[248:249], v[138:139], 0, s[22:23]
	s_add_u32 m0, s32, 0x12000
	v_lshl_add_u64 v[250:251], v[248:249], 0, s[48:49]
	global_load_lds_dwordx4 v[250:251], off
	s_barrier
	s_waitcnt lgkmcnt(0)
	v_mfma_f32_16x16x32_bf16 v[94:97], v[194:197], v[226:229], v[94:97]
	v_mfma_f32_16x16x32_bf16 v[90:93], v[194:197], v[234:237], v[90:93]
	v_mfma_f32_16x16x32_bf16 v[86:89], v[202:205], v[226:229], v[86:89]
	v_mfma_f32_16x16x32_bf16 v[82:85], v[202:205], v[234:237], v[82:85]
	v_mfma_f32_16x16x32_bf16 v[78:81], v[210:213], v[226:229], v[78:81]
	v_mfma_f32_16x16x32_bf16 v[74:77], v[210:213], v[234:237], v[74:77]
	v_mfma_f32_16x16x32_bf16 v[70:73], v[218:221], v[226:229], v[70:73]
	v_mfma_f32_16x16x32_bf16 v[66:69], v[218:221], v[234:237], v[66:69]
	v_mfma_f32_16x16x32_bf16 v[94:97], v[198:201], v[230:233], v[94:97]
	v_mfma_f32_16x16x32_bf16 v[90:93], v[198:201], v[238:241], v[90:93]
	v_mfma_f32_16x16x32_bf16 v[86:89], v[206:209], v[230:233], v[86:89]
	v_mfma_f32_16x16x32_bf16 v[82:85], v[206:209], v[238:241], v[82:85]
	v_mfma_f32_16x16x32_bf16 v[78:81], v[214:217], v[230:233], v[78:81]
	v_mfma_f32_16x16x32_bf16 v[74:77], v[214:217], v[238:241], v[74:77]
	v_mfma_f32_16x16x32_bf16 v[70:73], v[222:225], v[230:233], v[70:73]
	v_mfma_f32_16x16x32_bf16 v[66:69], v[222:225], v[238:241], v[66:69]
	v_lshl_add_u64 v[250:251], v[242:243], 0, s[82:83]
	s_mov_b32 m0, s32
	s_barrier
	ds_read_b128 v[194:197], v142 offset:16384
	ds_read_b128 v[198:201], v142 offset:17408
	ds_read_b128 v[202:205], v142 offset:18432
	ds_read_b128 v[206:209], v142 offset:19456
	ds_read_b128 v[210:213], v142 offset:20480
	ds_read_b128 v[214:217], v142 offset:21504
	ds_read_b128 v[218:221], v142 offset:22528
	ds_read_b128 v[222:225], v142 offset:23552
	global_load_lds_dwordx4 v[250:251], off
	s_add_u32 m0, s32, 0x2000
	v_lshl_add_u64 v[250:251], v[244:245], 0, s[82:83]
	global_load_lds_dwordx4 v[250:251], off
	s_barrier
	s_waitcnt lgkmcnt(0)
	v_mfma_f32_16x16x32_bf16 v[62:65], v[194:197], v[164:167], v[62:65]
	v_mfma_f32_16x16x32_bf16 v[58:61], v[194:197], v[186:189], v[58:61]
	v_mfma_f32_16x16x32_bf16 v[54:57], v[202:205], v[164:167], v[54:57]
	v_mfma_f32_16x16x32_bf16 v[50:53], v[202:205], v[186:189], v[50:53]
	v_mfma_f32_16x16x32_bf16 v[46:49], v[210:213], v[164:167], v[46:49]
	v_mfma_f32_16x16x32_bf16 v[42:45], v[210:213], v[186:189], v[42:45]
	v_mfma_f32_16x16x32_bf16 v[38:41], v[218:221], v[164:167], v[38:41]
	v_mfma_f32_16x16x32_bf16 v[34:37], v[218:221], v[186:189], v[34:37]
	v_mfma_f32_16x16x32_bf16 v[62:65], v[198:201], v[182:185], v[62:65]
	v_mfma_f32_16x16x32_bf16 v[58:61], v[198:201], v[190:193], v[58:61]
	v_mfma_f32_16x16x32_bf16 v[54:57], v[206:209], v[182:185], v[54:57]
	v_mfma_f32_16x16x32_bf16 v[50:53], v[206:209], v[190:193], v[50:53]
	v_mfma_f32_16x16x32_bf16 v[46:49], v[214:217], v[182:185], v[46:49]
	v_mfma_f32_16x16x32_bf16 v[42:45], v[214:217], v[190:193], v[42:45]
	v_mfma_f32_16x16x32_bf16 v[38:41], v[222:225], v[182:185], v[38:41]
	v_mfma_f32_16x16x32_bf16 v[34:37], v[222:225], v[190:193], v[34:37]
	s_barrier
	v_lshl_add_u64 v[164:165], v[246:247], 0, s[24:25]
	s_add_u32 m0, s32, 0x14000
	v_readfirstlane_b32 s0, v150
	global_load_lds_dwordx4 v[164:165], off
	s_mov_b32 m0, s0
	v_lshl_add_u64 v[164:165], v[248:249], 0, s[24:25]
	global_load_lds_dwordx4 v[164:165], off
	s_waitcnt vmcnt(6)
	s_barrier
	v_mfma_f32_16x16x32_bf16 v[30:33], v[194:197], v[226:229], v[30:33]
	v_mfma_f32_16x16x32_bf16 v[26:29], v[194:197], v[234:237], v[26:29]
	v_mfma_f32_16x16x32_bf16 v[22:25], v[202:205], v[226:229], v[22:25]
	v_mfma_f32_16x16x32_bf16 v[18:21], v[202:205], v[234:237], v[18:21]
	v_mfma_f32_16x16x32_bf16 v[14:17], v[210:213], v[226:229], v[14:17]
	v_mfma_f32_16x16x32_bf16 v[10:13], v[210:213], v[234:237], v[10:13]
	v_mfma_f32_16x16x32_bf16 v[6:9], v[218:221], v[226:229], v[6:9]
	v_mfma_f32_16x16x32_bf16 v[2:5], v[218:221], v[234:237], v[2:5]
	v_mfma_f32_16x16x32_bf16 v[30:33], v[198:201], v[230:233], v[30:33]
	v_mfma_f32_16x16x32_bf16 v[26:29], v[198:201], v[238:241], v[26:29]
	v_mfma_f32_16x16x32_bf16 v[22:25], v[206:209], v[230:233], v[22:25]
	v_mfma_f32_16x16x32_bf16 v[18:21], v[206:209], v[238:241], v[18:21]
	v_mfma_f32_16x16x32_bf16 v[14:17], v[214:217], v[230:233], v[14:17]
	v_mfma_f32_16x16x32_bf16 v[10:13], v[214:217], v[238:241], v[10:13]
	v_mfma_f32_16x16x32_bf16 v[6:9], v[222:225], v[230:233], v[6:9]
	v_mfma_f32_16x16x32_bf16 v[2:5], v[222:225], v[238:241], v[2:5]
	s_barrier
	ds_read_b128 v[164:167], v149
	ds_read_b128 v[182:185], v149 offset:1024
	ds_read_b128 v[186:189], v149 offset:2048
	ds_read_b128 v[190:193], v149 offset:3072
	v_readfirstlane_b32 s0, v151
	v_lshl_add_u64 v[226:227], v[242:243], 0, s[86:87]
	s_mov_b32 m0, s0
	v_readfirstlane_b32 s0, v152
	ds_read_b128 v[194:197], v142 offset:32768
	ds_read_b128 v[198:201], v142 offset:33792
	ds_read_b128 v[202:205], v142 offset:34816
	ds_read_b128 v[206:209], v142 offset:35840
	ds_read_b128 v[210:213], v142 offset:36864
	ds_read_b128 v[214:217], v142 offset:37888
	ds_read_b128 v[218:221], v142 offset:38912
	ds_read_b128 v[222:225], v142 offset:39936
	global_load_lds_dwordx4 v[226:227], off
	s_mov_b32 m0, s0
	v_lshl_add_u64 v[226:227], v[244:245], 0, s[86:87]
	global_load_lds_dwordx4 v[226:227], off
	s_waitcnt lgkmcnt(8)
	s_barrier
; #define G_LDA(dst, b, h)                                                                                                  \
;   _Pragma("unroll") for (int m = 0; m < 4; ++m) _Pragma("unroll") for (int k = 0; k < 2; ++k)                             \
;       dst[m][k] = *(const bf16x8*)((const char*)G_SA(b, h) + ((wr * 4 + m) * 2 + k) * 1024 + rdo)
; #define G_LDB(dst, b, h)                                                                                                  \
;   _Pragma("unroll") for (int n = 0; n < 2; ++n) _Pragma("unroll") for (int k = 0; k < 2; ++k)                             \
;       dst[n][k] = *(const bf16x8*)((const char*)G_SB(b, h) + ((wc * 2 + n) * 2 + k) * 1024 + rdo)
; #define G_WAIT_V(n) asm volatile("s_waitcnt vmcnt(" #n ")" ::: "memory")
; #define G_WAIT_L(n) asm volatile("s_waitcnt lgkmcnt(" #n ")" ::: "memory")
; #define G_BAR __builtin_amdgcn_s_barrier()
; #define G_SCHED __builtin_amdgcn_sched_barrier(0)
; DI void br_flush(PREF p, f32x4 (&acc)[2][2][4][2], int slot) { br_store(p, acc, slot); zero_acc256(acc); }
;     ...
;     G_WAIT_L(8); G_BAR; G_WAIT_L(0); G_MMA(0, 0, At, B0); G_BAR; G_SCHED;
;     G_LDB(B1, 1, 1); G_STAGE(G_SB(1, 0), B, ob0, ob1, LDB, 0, KB(tt + 3));
;     G_BAR; G_WAIT_L(0); G_MMA(0, 1, At, B1); G_BAR;
;     G_LDA(At, 1, 1); G_STAGE(G_SA(1, 0), A, oa0, oa1, LDA, 0, KA(tt + 3));
;     G_BAR; G_WAIT_L(0); G_MMA(1, 0, At, B0); G_BAR; G_SCHED;
;     G_STAGE(G_SB(1, 1), B, ob0, ob1, LDB, 128, KB(tt + 3));
;     G_WAIT_V(6); G_BAR; G_MMA(1, 1, At, B1); G_BAR;
;     if (MODE && ((tt + 1) & 3) == 3) br_flush(p, acc, (tt + 1) >> 2);
;   }
	s_waitcnt lgkmcnt(0)
	v_mfma_f32_16x16x32_bf16 v[126:129], v[194:197], v[164:167], v[126:129]
	v_mfma_f32_16x16x32_bf16 v[122:125], v[194:197], v[186:189], v[122:125]
	v_mfma_f32_16x16x32_bf16 v[118:121], v[202:205], v[164:167], v[118:121]
	v_mfma_f32_16x16x32_bf16 v[114:117], v[202:205], v[186:189], v[114:117]
	v_mfma_f32_16x16x32_bf16 v[110:113], v[210:213], v[164:167], v[110:113]
	v_mfma_f32_16x16x32_bf16 v[106:109], v[210:213], v[186:189], v[106:109]
	v_mfma_f32_16x16x32_bf16 v[102:105], v[218:221], v[164:167], v[102:105]
	v_mfma_f32_16x16x32_bf16 v[98:101], v[218:221], v[186:189], v[98:101]
	v_mfma_f32_16x16x32_bf16 v[126:129], v[198:201], v[182:185], v[126:129]
	v_mfma_f32_16x16x32_bf16 v[122:125], v[198:201], v[190:193], v[122:125]
	v_mfma_f32_16x16x32_bf16 v[118:121], v[206:209], v[182:185], v[118:121]
	v_mfma_f32_16x16x32_bf16 v[114:117], v[206:209], v[190:193], v[114:117]
	v_mfma_f32_16x16x32_bf16 v[110:113], v[214:217], v[182:185], v[110:113]
	v_mfma_f32_16x16x32_bf16 v[106:109], v[214:217], v[190:193], v[106:109]
	v_mfma_f32_16x16x32_bf16 v[102:105], v[222:225], v[182:185], v[102:105]
	v_mfma_f32_16x16x32_bf16 v[98:101], v[222:225], v[190:193], v[98:101]
	s_barrier
	v_readfirstlane_b32 s0, v153
	v_lshl_add_u64 v[250:251], v[246:247], 0, s[26:27]
	s_mov_b32 m0, s0
	v_readfirstlane_b32 s0, v154
	ds_read_b128 v[226:229], v145
	ds_read_b128 v[230:233], v145 offset:1024
	ds_read_b128 v[234:237], v145 offset:2048
	ds_read_b128 v[238:241], v145 offset:3072
	global_load_lds_dwordx4 v[250:251], off
	s_mov_b32 m0, s0
	v_lshl_add_u64 v[250:251], v[248:249], 0, s[26:27]
	global_load_lds_dwordx4 v[250:251], off
	s_barrier
	s_waitcnt lgkmcnt(0)
	v_mfma_f32_16x16x32_bf16 v[94:97], v[194:197], v[226:229], v[94:97]
	v_mfma_f32_16x16x32_bf16 v[90:93], v[194:197], v[234:237], v[90:93]
	v_mfma_f32_16x16x32_bf16 v[86:89], v[202:205], v[226:229], v[86:89]
	v_mfma_f32_16x16x32_bf16 v[82:85], v[202:205], v[234:237], v[82:85]
	v_mfma_f32_16x16x32_bf16 v[78:81], v[210:213], v[226:229], v[78:81]
	v_mfma_f32_16x16x32_bf16 v[74:77], v[210:213], v[234:237], v[74:77]
	v_mfma_f32_16x16x32_bf16 v[70:73], v[218:221], v[226:229], v[70:73]
	v_mfma_f32_16x16x32_bf16 v[66:69], v[218:221], v[234:237], v[66:69]
	v_mfma_f32_16x16x32_bf16 v[94:97], v[198:201], v[230:233], v[94:97]
	v_mfma_f32_16x16x32_bf16 v[90:93], v[198:201], v[238:241], v[90:93]
	v_mfma_f32_16x16x32_bf16 v[86:89], v[206:209], v[230:233], v[86:89]
	v_mfma_f32_16x16x32_bf16 v[82:85], v[206:209], v[238:241], v[82:85]
	v_mfma_f32_16x16x32_bf16 v[78:81], v[214:217], v[230:233], v[78:81]
	v_mfma_f32_16x16x32_bf16 v[74:77], v[214:217], v[238:241], v[74:77]
	v_mfma_f32_16x16x32_bf16 v[70:73], v[222:225], v[230:233], v[70:73]
	v_mfma_f32_16x16x32_bf16 v[66:69], v[222:225], v[238:241], v[66:69]
	v_readfirstlane_b32 s0, v155
	v_lshl_add_u64 v[242:243], v[242:243], 0, s[90:91]
	s_mov_b32 m0, s0
	v_readfirstlane_b32 s0, v156
	s_barrier
	ds_read_b128 v[194:197], v142 offset:49152
	ds_read_b128 v[198:201], v142 offset:50176
	ds_read_b128 v[202:205], v142 offset:51200
	ds_read_b128 v[206:209], v142 offset:52224
	ds_read_b128 v[210:213], v142 offset:53248
	ds_read_b128 v[214:217], v142 offset:54272
	ds_read_b128 v[218:221], v142 offset:55296
	ds_read_b128 v[222:225], v142 offset:56320
	global_load_lds_dwordx4 v[242:243], off
	s_mov_b32 m0, s0
	v_lshl_add_u64 v[242:243], v[244:245], 0, s[90:91]
	global_load_lds_dwordx4 v[242:243], off
	s_barrier
	s_waitcnt lgkmcnt(0)
	v_mfma_f32_16x16x32_bf16 v[62:65], v[194:197], v[164:167], v[62:65]
	v_mfma_f32_16x16x32_bf16 v[58:61], v[194:197], v[186:189], v[58:61]
	v_mfma_f32_16x16x32_bf16 v[54:57], v[202:205], v[164:167], v[54:57]
	v_mfma_f32_16x16x32_bf16 v[50:53], v[202:205], v[186:189], v[50:53]
	v_mfma_f32_16x16x32_bf16 v[46:49], v[210:213], v[164:167], v[46:49]
	v_mfma_f32_16x16x32_bf16 v[42:45], v[210:213], v[186:189], v[42:45]
	v_mfma_f32_16x16x32_bf16 v[38:41], v[218:221], v[164:167], v[38:41]
	v_mfma_f32_16x16x32_bf16 v[34:37], v[218:221], v[186:189], v[34:37]
	v_mfma_f32_16x16x32_bf16 v[62:65], v[198:201], v[182:185], v[62:65]
	v_mfma_f32_16x16x32_bf16 v[58:61], v[198:201], v[190:193], v[58:61]
	v_mfma_f32_16x16x32_bf16 v[54:57], v[206:209], v[182:185], v[54:57]
	v_mfma_f32_16x16x32_bf16 v[50:53], v[206:209], v[190:193], v[50:53]
	v_mfma_f32_16x16x32_bf16 v[46:49], v[214:217], v[182:185], v[46:49]
	v_mfma_f32_16x16x32_bf16 v[42:45], v[214:217], v[190:193], v[42:45]
	v_mfma_f32_16x16x32_bf16 v[38:41], v[222:225], v[182:185], v[38:41]
	v_mfma_f32_16x16x32_bf16 v[34:37], v[222:225], v[190:193], v[34:37]
	s_barrier
	v_readfirstlane_b32 s0, v157
	v_lshl_add_u64 v[164:165], v[246:247], 0, s[36:37]
	s_mov_b32 m0, s0
	s_nop 0
	global_load_lds_dwordx4 v[164:165], off
	s_add_u32 m0, s32, 0x1e000
	v_lshl_add_u64 v[164:165], v[248:249], 0, s[36:37]
	global_load_lds_dwordx4 v[164:165], off
	s_waitcnt vmcnt(6)
	s_barrier
	v_mfma_f32_16x16x32_bf16 v[30:33], v[194:197], v[226:229], v[30:33]
	v_mfma_f32_16x16x32_bf16 v[26:29], v[194:197], v[234:237], v[26:29]
	v_mfma_f32_16x16x32_bf16 v[22:25], v[202:205], v[226:229], v[22:25]
	v_mfma_f32_16x16x32_bf16 v[18:21], v[202:205], v[234:237], v[18:21]
	v_mfma_f32_16x16x32_bf16 v[14:17], v[210:213], v[226:229], v[14:17]
	v_mfma_f32_16x16x32_bf16 v[10:13], v[210:213], v[234:237], v[10:13]
	v_mfma_f32_16x16x32_bf16 v[6:9], v[218:221], v[226:229], v[6:9]
	v_mfma_f32_16x16x32_bf16 v[2:5], v[218:221], v[234:237], v[2:5]
	v_mfma_f32_16x16x32_bf16 v[30:33], v[198:201], v[230:233], v[30:33]
	v_mfma_f32_16x16x32_bf16 v[26:29], v[198:201], v[238:241], v[26:29]
	v_mfma_f32_16x16x32_bf16 v[22:25], v[206:209], v[230:233], v[22:25]
	v_mfma_f32_16x16x32_bf16 v[18:21], v[206:209], v[238:241], v[18:21]
	v_mfma_f32_16x16x32_bf16 v[14:17], v[214:217], v[230:233], v[14:17]
	v_mfma_f32_16x16x32_bf16 v[10:13], v[214:217], v[238:241], v[10:13]
	v_mfma_f32_16x16x32_bf16 v[6:9], v[222:225], v[230:233], v[6:9]
	v_mfma_f32_16x16x32_bf16 v[2:5], v[222:225], v[238:241], v[2:5]
	s_add_i32 s9, s9, 2
	s_add_u32 s22, s22, 0x100
	s_addc_u32 s23, s23, 0
	s_cmp_lt_u32 s9, 12
	s_barrier
; #define G_LDA(dst, b, h)                                                                                                  \
;   _Pragma("unroll") for (int m = 0; m < 4; ++m) _Pragma("unroll") for (int k = 0; k < 2; ++k)                             \
;       dst[m][k] = *(const bf16x8*)((const char*)G_SA(b, h) + ((wr * 4 + m) * 2 + k) * 1024 + rdo)
; #define G_LDB(dst, b, h)                                                                                                  \
;   _Pragma("unroll") for (int n = 0; n < 2; ++n) _Pragma("unroll") for (int k = 0; k < 2; ++k)                             \
;       dst[n][k] = *(const bf16x8*)((const char*)G_SB(b, h) + ((wc * 2 + n) * 2 + k) * 1024 + rdo)
; #define G_WAIT_V(n) asm volatile("s_waitcnt vmcnt(" #n ")" ::: "memory")
; #define G_WAIT_L(n) asm volatile("s_waitcnt lgkmcnt(" #n ")" ::: "memory")
; #define G_BAR __builtin_amdgcn_s_barrier()
;     ...
;   }
;   {
;     G_LDB(B0, 0, 0); G_LDA(At, 0, 0); G_STAGE(G_SA(1, 1), A, oa0, oa1, LDA, 128, KA(nt - 1));
;     G_BAR; G_WAIT_L(0); G_MMA(0, 0, At, B0); G_BAR;
;     G_LDB(B1, 0, 1); G_BAR; G_WAIT_L(0); G_MMA(0, 1, At, B1); G_BAR;
;     G_LDA(At, 0, 1); G_WAIT_V(4); G_BAR; G_WAIT_L(0); G_MMA(1, 0, At, B0); G_MMA(1, 1, At, B1); G_BAR;
	s_cbranch_scc1 .LBB0_66
	s_add_u32 s0, s20, 0x40780
	s_addc_u32 s1, s21, 0
	v_lshl_add_u64 v[132:133], v[132:133], 1, s[0:1]
	s_add_u32 m0, s32, 0xc000
	v_lshl_add_u64 v[130:131], v[130:131], 1, s[0:1]
	ds_read_b128 v[134:137], v160
	ds_read_b128 v[138:141], v160 offset:1024
	ds_read_b128 v[150:153], v160 offset:2048
	ds_read_b128 v[154:157], v160 offset:3072
	ds_read_b128 v[164:167], v142
	ds_read_b128 v[182:185], v142 offset:1024
	ds_read_b128 v[186:189], v142 offset:2048
	ds_read_b128 v[190:193], v142 offset:3072
	ds_read_b128 v[194:197], v142 offset:4096
	ds_read_b128 v[198:201], v142 offset:5120
	ds_read_b128 v[202:205], v142 offset:6144
	ds_read_b128 v[206:209], v142 offset:7168
	global_load_lds_dwordx4 v[132:133], off
	s_add_u32 m0, s32, 0xe000
	s_nop 0
	global_load_lds_dwordx4 v[130:131], off
	s_barrier
	s_waitcnt lgkmcnt(0)
	v_mfma_f32_16x16x32_bf16 v[126:129], v[164:167], v[134:137], v[126:129]
	v_mfma_f32_16x16x32_bf16 v[122:125], v[164:167], v[150:153], v[122:125]
	v_mfma_f32_16x16x32_bf16 v[110:113], v[194:197], v[134:137], v[110:113]
	v_mfma_f32_16x16x32_bf16 v[102:105], v[202:205], v[134:137], v[102:105]
	v_mfma_f32_16x16x32_bf16 v[126:129], v[182:185], v[138:141], v[126:129]
	v_mfma_f32_16x16x32_bf16 v[122:125], v[182:185], v[154:157], v[122:125]
	v_mfma_f32_16x16x32_bf16 v[118:121], v[186:189], v[134:137], v[118:121]
	v_mfma_f32_16x16x32_bf16 v[114:117], v[186:189], v[150:153], v[114:117]
	v_mfma_f32_16x16x32_bf16 v[110:113], v[198:201], v[138:141], v[110:113]
	v_mfma_f32_16x16x32_bf16 v[106:109], v[194:197], v[150:153], v[106:109]
	v_mfma_f32_16x16x32_bf16 v[102:105], v[206:209], v[138:141], v[102:105]
	v_mfma_f32_16x16x32_bf16 v[98:101], v[202:205], v[150:153], v[98:101]
	v_mfma_f32_16x16x32_bf16 v[130:133], v[190:193], v[138:141], v[118:121]
	v_mfma_f32_16x16x32_bf16 v[210:213], v[190:193], v[154:157], v[114:117]
	v_mfma_f32_16x16x32_bf16 v[214:217], v[198:201], v[154:157], v[106:109]
	v_mfma_f32_16x16x32_bf16 v[218:221], v[206:209], v[154:157], v[98:101]
	s_barrier
	s_nop 1
	s_nop 0
	ds_read_b128 v[98:101], v158
	ds_read_b128 v[106:109], v158 offset:1024
	ds_read_b128 v[114:117], v158 offset:2048
	ds_read_b128 v[118:121], v158 offset:3072
	s_barrier
	s_waitcnt lgkmcnt(0)
	v_mfma_f32_16x16x32_bf16 v[94:97], v[164:167], v[98:101], v[94:97]
	v_mfma_f32_16x16x32_bf16 v[90:93], v[164:167], v[114:117], v[90:93]
	v_mfma_f32_16x16x32_bf16 v[78:81], v[194:197], v[98:101], v[78:81]
	v_mfma_f32_16x16x32_bf16 v[70:73], v[202:205], v[98:101], v[70:73]
	v_mfma_f32_16x16x32_bf16 v[94:97], v[182:185], v[106:109], v[94:97]
	v_mfma_f32_16x16x32_bf16 v[90:93], v[182:185], v[118:121], v[90:93]
	v_mfma_f32_16x16x32_bf16 v[86:89], v[186:189], v[98:101], v[86:89]
	v_mfma_f32_16x16x32_bf16 v[82:85], v[186:189], v[114:117], v[82:85]
	v_mfma_f32_16x16x32_bf16 v[78:81], v[198:201], v[106:109], v[78:81]
	v_mfma_f32_16x16x32_bf16 v[74:77], v[194:197], v[114:117], v[74:77]
	v_mfma_f32_16x16x32_bf16 v[70:73], v[206:209], v[106:109], v[70:73]
	v_mfma_f32_16x16x32_bf16 v[66:69], v[202:205], v[114:117], v[66:69]
	v_mfma_f32_16x16x32_bf16 v[158:161], v[190:193], v[106:109], v[86:89]
	v_mfma_f32_16x16x32_bf16 v[164:167], v[190:193], v[118:121], v[82:85]
	v_mfma_f32_16x16x32_bf16 v[182:185], v[198:201], v[118:121], v[74:77]
	v_mfma_f32_16x16x32_bf16 v[186:189], v[206:209], v[118:121], v[66:69]
	s_barrier
	s_nop 1
	s_nop 0
	ds_read_b128 v[66:69], v142 offset:16384
	ds_read_b128 v[74:77], v142 offset:17408
	ds_read_b128 v[82:85], v142 offset:18432
	ds_read_b128 v[86:89], v142 offset:19456
	ds_read_b128 v[190:193], v142 offset:20480
	ds_read_b128 v[194:197], v142 offset:21504
	ds_read_b128 v[198:201], v142 offset:22528
	ds_read_b128 v[202:205], v142 offset:23552
	s_waitcnt vmcnt(4)
	s_barrier
	s_waitcnt lgkmcnt(0)
	v_mfma_f32_16x16x32_bf16 v[62:65], v[66:69], v[134:137], v[62:65]
	v_mfma_f32_16x16x32_bf16 v[58:61], v[66:69], v[150:153], v[58:61]
	v_mfma_f32_16x16x32_bf16 v[46:49], v[190:193], v[134:137], v[46:49]
	v_mfma_f32_16x16x32_bf16 v[38:41], v[198:201], v[134:137], v[38:41]
	v_mfma_f32_16x16x32_bf16 v[62:65], v[74:77], v[138:141], v[62:65]
	v_mfma_f32_16x16x32_bf16 v[58:61], v[74:77], v[154:157], v[58:61]
	v_mfma_f32_16x16x32_bf16 v[54:57], v[82:85], v[134:137], v[54:57]
	v_mfma_f32_16x16x32_bf16 v[50:53], v[82:85], v[150:153], v[50:53]
	v_mfma_f32_16x16x32_bf16 v[46:49], v[194:197], v[138:141], v[46:49]
	v_mfma_f32_16x16x32_bf16 v[42:45], v[190:193], v[150:153], v[42:45]
	v_mfma_f32_16x16x32_bf16 v[38:41], v[202:205], v[138:141], v[38:41]
	v_mfma_f32_16x16x32_bf16 v[34:37], v[198:201], v[150:153], v[34:37]
	v_mfma_f32_16x16x32_bf16 v[206:209], v[86:89], v[138:141], v[54:57]
	v_mfma_f32_16x16x32_bf16 v[222:225], v[86:89], v[154:157], v[50:53]
	v_mfma_f32_16x16x32_bf16 v[226:229], v[194:197], v[154:157], v[42:45]
	v_mfma_f32_16x16x32_bf16 v[134:137], v[202:205], v[154:157], v[34:37]
	v_mfma_f32_16x16x32_bf16 v[30:33], v[66:69], v[98:101], v[30:33]
	v_mfma_f32_16x16x32_bf16 v[26:29], v[66:69], v[114:117], v[26:29]
	v_mfma_f32_16x16x32_bf16 v[14:17], v[190:193], v[98:101], v[14:17]
	v_mfma_f32_16x16x32_bf16 v[6:9], v[198:201], v[98:101], v[6:9]
	v_mfma_f32_16x16x32_bf16 v[30:33], v[74:77], v[106:109], v[30:33]
	v_mfma_f32_16x16x32_bf16 v[26:29], v[74:77], v[118:121], v[26:29]
	v_mfma_f32_16x16x32_bf16 v[22:25], v[82:85], v[98:101], v[22:25]
	v_mfma_f32_16x16x32_bf16 v[18:21], v[82:85], v[114:117], v[18:21]
	v_mfma_f32_16x16x32_bf16 v[14:17], v[194:197], v[106:109], v[14:17]
	v_mfma_f32_16x16x32_bf16 v[10:13], v[190:193], v[114:117], v[10:13]
	v_mfma_f32_16x16x32_bf16 v[6:9], v[202:205], v[106:109], v[6:9]
	v_mfma_f32_16x16x32_bf16 v[2:5], v[198:201], v[114:117], v[2:5]
	v_mfma_f32_16x16x32_bf16 v[138:141], v[86:89], v[106:109], v[22:25]
	v_mfma_f32_16x16x32_bf16 v[150:153], v[86:89], v[118:121], v[18:21]
	v_mfma_f32_16x16x32_bf16 v[154:157], v[194:197], v[118:121], v[10:13]
	v_mfma_f32_16x16x32_bf16 v[190:193], v[202:205], v[118:121], v[2:5]
	s_barrier
; #define G_LDA(dst, b, h)                                                                                                  \
;   _Pragma("unroll") for (int m = 0; m < 4; ++m) _Pragma("unroll") for (int k = 0; k < 2; ++k)                             \
;       dst[m][k] = *(const bf16x8*)((const char*)G_SA(b, h) + ((wr * 4 + m) * 2 + k) * 1024 + rdo)
; #define G_LDB(dst, b, h)                                                                                                  \
;   _Pragma("unroll") for (int n = 0; n < 2; ++n) _Pragma("unroll") for (int k = 0; k < 2; ++k)                             \
;       dst[n][k] = *(const bf16x8*)((const char*)G_SB(b, h) + ((wc * 2 + n) * 2 + k) * 1024 + rdo)
; #define G_WAIT_V(n) asm volatile("s_waitcnt vmcnt(" #n ")" ::: "memory")
; #define G_WAIT_L(n) asm volatile("s_waitcnt lgkmcnt(" #n ")" ::: "memory")
; #define G_BAR __builtin_amdgcn_s_barrier()
;     ...
;     G_LDA(At, 0, 1); G_WAIT_V(4); G_BAR; G_WAIT_L(0); G_MMA(1, 0, At, B0); G_MMA(1, 1, At, B1); G_BAR;
;   }
;   {
;     G_LDB(B0, 1, 0); G_LDA(At, 1, 0); G_WAIT_V(2); G_BAR; G_WAIT_L(0); G_MMA(0, 0, At, B0); G_BAR;
;     G_LDB(B1, 1, 1); G_WAIT_V(0); G_BAR; G_WAIT_L(0); G_MMA(0, 1, At, B1); G_BAR;
;     G_LDA(At, 1, 1); G_BAR; G_WAIT_L(0); G_MMA(1, 0, At, B0); G_MMA(1, 1, At, B1); G_BAR;
;   }
;   if (wr == 0) G_BAR;
	s_nop 1
	s_nop 0
	ds_read_b128 v[2:5], v149
	ds_read_b128 v[10:13], v149 offset:1024
	ds_read_b128 v[18:21], v149 offset:2048
	ds_read_b128 v[22:25], v149 offset:3072
	ds_read_b128 v[34:37], v142 offset:32768
	ds_read_b128 v[42:45], v142 offset:33792
	ds_read_b128 v[50:53], v142 offset:34816
	ds_read_b128 v[54:57], v142 offset:35840
	ds_read_b128 v[66:69], v142 offset:36864
	ds_read_b128 v[146:149], v142 offset:37888
	ds_read_b128 v[194:197], v142 offset:38912
	ds_read_b128 v[198:201], v142 offset:39936
	s_waitcnt vmcnt(2)
	s_barrier
	s_waitcnt lgkmcnt(0)
	v_mfma_f32_16x16x32_bf16 v[74:77], v[34:37], v[2:5], v[126:129]
	v_mfma_f32_16x16x32_bf16 v[118:121], v[42:45], v[10:13], v[74:77]
	v_mfma_f32_16x16x32_bf16 v[74:77], v[34:37], v[18:21], v[122:125]
	v_mfma_f32_16x16x32_bf16 v[126:129], v[42:45], v[22:25], v[74:77]
	v_mfma_f32_16x16x32_bf16 v[74:77], v[50:53], v[2:5], v[130:133]
	v_mfma_f32_16x16x32_bf16 v[114:117], v[54:57], v[10:13], v[74:77]
	v_mfma_f32_16x16x32_bf16 v[74:77], v[50:53], v[18:21], v[210:213]
	v_mfma_f32_16x16x32_bf16 v[122:125], v[54:57], v[22:25], v[74:77]
	v_mfma_f32_16x16x32_bf16 v[74:77], v[66:69], v[2:5], v[110:113]
	v_mfma_f32_16x16x32_bf16 v[106:109], v[146:149], v[10:13], v[74:77]
	v_mfma_f32_16x16x32_bf16 v[74:77], v[66:69], v[18:21], v[214:217]
	v_mfma_f32_16x16x32_bf16 v[110:113], v[146:149], v[22:25], v[74:77]
	v_mfma_f32_16x16x32_bf16 v[74:77], v[194:197], v[2:5], v[102:105]
	v_mfma_f32_16x16x32_bf16 v[98:101], v[198:201], v[10:13], v[74:77]
	v_mfma_f32_16x16x32_bf16 v[74:77], v[194:197], v[18:21], v[218:221]
	v_mfma_f32_16x16x32_bf16 v[102:105], v[198:201], v[22:25], v[74:77]
	s_barrier
	ds_read_b128 v[130:133], v145
	ds_read_b128 v[202:205], v145 offset:1024
	ds_read_b128 v[210:213], v145 offset:2048
	ds_read_b128 v[214:217], v145 offset:3072
	s_waitcnt vmcnt(0)
	s_barrier
	s_waitcnt lgkmcnt(0)
	v_mfma_f32_16x16x32_bf16 v[74:77], v[34:37], v[130:133], v[94:97]
	v_mfma_f32_16x16x32_bf16 v[34:37], v[34:37], v[210:213], v[90:93]
	v_mfma_f32_16x16x32_bf16 v[94:97], v[42:45], v[214:217], v[34:37]
	v_mfma_f32_16x16x32_bf16 v[34:37], v[50:53], v[130:133], v[158:161]
	v_mfma_f32_16x16x32_bf16 v[82:85], v[54:57], v[202:205], v[34:37]
	v_mfma_f32_16x16x32_bf16 v[34:37], v[50:53], v[210:213], v[164:167]
	v_mfma_f32_16x16x32_bf16 v[90:93], v[54:57], v[214:217], v[34:37]
	v_mfma_f32_16x16x32_bf16 v[34:37], v[66:69], v[130:133], v[78:81]
	v_mfma_f32_16x16x32_bf16 v[86:89], v[42:45], v[202:205], v[74:77]
	v_mfma_f32_16x16x32_bf16 v[74:77], v[146:149], v[202:205], v[34:37]
	v_mfma_f32_16x16x32_bf16 v[34:37], v[66:69], v[210:213], v[182:185]
	v_mfma_f32_16x16x32_bf16 v[78:81], v[146:149], v[214:217], v[34:37]
	v_mfma_f32_16x16x32_bf16 v[34:37], v[194:197], v[130:133], v[70:73]
	v_mfma_f32_16x16x32_bf16 v[66:69], v[198:201], v[202:205], v[34:37]
	v_mfma_f32_16x16x32_bf16 v[34:37], v[194:197], v[210:213], v[186:189]
	v_mfma_f32_16x16x32_bf16 v[70:73], v[198:201], v[214:217], v[34:37]
	s_barrier
	ds_read_b128 v[144:147], v142 offset:49152
	ds_read_b128 v[158:161], v142 offset:50176
	ds_read_b128 v[164:167], v142 offset:51200
	ds_read_b128 v[182:185], v142 offset:52224
	ds_read_b128 v[186:189], v142 offset:53248
	ds_read_b128 v[194:197], v142 offset:54272
	ds_read_b128 v[198:201], v142 offset:55296
	ds_read_b128 v[218:221], v142 offset:56320
	s_barrier
	s_waitcnt lgkmcnt(0)
	v_mfma_f32_16x16x32_bf16 v[34:37], v[144:147], v[2:5], v[62:65]
	v_mfma_f32_16x16x32_bf16 v[54:57], v[158:161], v[10:13], v[34:37]
	v_mfma_f32_16x16x32_bf16 v[34:37], v[144:147], v[18:21], v[58:61]
	v_mfma_f32_16x16x32_bf16 v[62:65], v[158:161], v[22:25], v[34:37]
	v_mfma_f32_16x16x32_bf16 v[34:37], v[164:167], v[2:5], v[206:209]
	v_mfma_f32_16x16x32_bf16 v[50:53], v[182:185], v[10:13], v[34:37]
	v_mfma_f32_16x16x32_bf16 v[34:37], v[164:167], v[18:21], v[222:225]
	v_mfma_f32_16x16x32_bf16 v[58:61], v[182:185], v[22:25], v[34:37]
	v_mfma_f32_16x16x32_bf16 v[34:37], v[186:189], v[2:5], v[46:49]
	v_mfma_f32_16x16x32_bf16 v[42:45], v[194:197], v[10:13], v[34:37]
	v_mfma_f32_16x16x32_bf16 v[34:37], v[186:189], v[18:21], v[226:229]
	v_mfma_f32_16x16x32_bf16 v[2:5], v[198:201], v[2:5], v[38:41]
	v_mfma_f32_16x16x32_bf16 v[46:49], v[194:197], v[22:25], v[34:37]
	v_mfma_f32_16x16x32_bf16 v[34:37], v[218:221], v[10:13], v[2:5]
	v_mfma_f32_16x16x32_bf16 v[2:5], v[198:201], v[18:21], v[134:137]
	v_mfma_f32_16x16x32_bf16 v[38:41], v[218:221], v[22:25], v[2:5]
	v_mfma_f32_16x16x32_bf16 v[2:5], v[144:147], v[130:133], v[30:33]
	v_mfma_f32_16x16x32_bf16 v[22:25], v[158:161], v[202:205], v[2:5]
	v_mfma_f32_16x16x32_bf16 v[2:5], v[144:147], v[210:213], v[26:29]
	v_mfma_f32_16x16x32_bf16 v[30:33], v[158:161], v[214:217], v[2:5]
	v_mfma_f32_16x16x32_bf16 v[2:5], v[164:167], v[130:133], v[138:141]
	v_mfma_f32_16x16x32_bf16 v[18:21], v[182:185], v[202:205], v[2:5]
	v_mfma_f32_16x16x32_bf16 v[2:5], v[164:167], v[210:213], v[150:153]
	v_mfma_f32_16x16x32_bf16 v[26:29], v[182:185], v[214:217], v[2:5]
	v_mfma_f32_16x16x32_bf16 v[2:5], v[186:189], v[130:133], v[14:17]
	v_mfma_f32_16x16x32_bf16 v[10:13], v[194:197], v[202:205], v[2:5]
	v_mfma_f32_16x16x32_bf16 v[2:5], v[186:189], v[210:213], v[154:157]
	v_mfma_f32_16x16x32_bf16 v[14:17], v[194:197], v[214:217], v[2:5]
	v_mfma_f32_16x16x32_bf16 v[2:5], v[198:201], v[130:133], v[6:9]
	v_mfma_f32_16x16x32_bf16 v[6:9], v[198:201], v[210:213], v[190:193]
	v_mfma_f32_16x16x32_bf16 v[2:5], v[218:221], v[202:205], v[2:5]
	v_mfma_f32_16x16x32_bf16 v[6:9], v[218:221], v[214:217], v[6:9]
	v_cmp_gt_u32_e32 vcc, s67, v0
	s_barrier
	s_and_saveexec_b64 s[20:21], vcc
	s_cbranch_execz .LBB0_69
	s_barrier

; DI void lds_barrier() { asm volatile("s_waitcnt lgkmcnt(0)\n\ts_barrier" ::: "memory"); }
; DI int tid512() { int t = threadIdx.x; asm volatile("" : "+v"(t)); return t; }
; #define G_WAIT_V(n) asm volatile("s_waitcnt vmcnt(" #n ")" ::: "memory")
; #define G_BAR __builtin_amdgcn_s_barrier()
;     ...
;   const int t = tid512();
;   const int wid = t >> 6, lane = t & 63, wr = wid >> 2, wc = wid & 3, fr = lane & 15, fq = lane >> 4;
;   int r0, c0, r1, c1;
;   g_stage_rc(t * 16, r0, c0); g_stage_rc(t * 16 + 8192, r1, c1);
;   const int oa0 = r0 * LDA + c0, oa1 = r1 * LDA + c1, ob0 = r0 * LDB + c0, ob1 = r1 * LDB + c1;
;   const int obr = fr * 64 + fq * 16, rdo = obr ^ (((obr >> 9) & 1) << 5);
;   bf16x8 At[4][2], B0[2][2], B1[2][2];
;   constexpr int nt = K / 64;
;   lds_barrier();
;   G_STAGE(G_SB(0, 0), B, ob0, ob1, LDB, 0, KB(0)); G_STAGE(G_SA(0, 0), A, oa0, oa1, LDA, 0, KA(0));
;   G_STAGE(G_SB(0, 1), B, ob0, ob1, LDB, 128, KB(0)); G_STAGE(G_SA(0, 1), A, oa0, oa1, LDA, 128, KA(0));
;   if (wr == 1) G_BAR;
;   G_WAIT_V(4); G_BAR;
;   G_STAGE(G_SB(1, 0), B, ob0, ob1, LDB, 0, KB(1)); G_STAGE(G_SA(1, 0), A, oa0, oa1, LDA, 0, KA(1)); G_STAGE(G_SB(1, 1), B, ob0, ob1, LDB, 128, KB(1));
;   G_WAIT_V(6); G_BAR;
; DI void zero_acc256(f32x4 (&a)[2][2][4][2]) {
; #pragma unroll
;   for (int i = 0; i < 2; ++i)
; #pragma unroll
;     for (int j = 0; j < 2; ++j)
; #pragma unroll
;       for (int m = 0; m < 4; ++m)
; #pragma unroll
;         for (int n = 0; n < 2; ++n)
; #pragma unroll
;           for (int e = 0; e < 4; ++e) a[i][j][m][n][e] = 0.f;
; }
.LBB0_102:
	s_lshl_b32 s52, s23, 6
	s_add_u32 s0, s52, s28
	v_mov_b32_e32 v0, v168
	s_addc_u32 s1, 0, s29
	s_lshl_b64 s[0:1], s[0:1], 11
	v_lshlrev_b32_e32 v143, 4, v0
	s_nop 0
	v_readfirstlane_b32 s32, v143
	v_and_b32_e32 v2, 32, v0
	v_lshrrev_b32_e32 v4, 1, v0
	v_bitop3_b32 v2, v143, v2, 48 bitop3:0x6c
	s_add_u32 s8, s65, s0
	v_ashrrev_i32_e32 v10, 3, v0
	v_bfe_u32 v13, v0, 2, 4
	s_mov_b32 s0, 0x3ffff0
	v_and_b32_e32 v11, 32, v4
	v_lshrrev_b32_e32 v12, 1, v2
	v_add_u32_e32 v144, 0x2000, v143
	v_and_or_b32 v3, v10, s0, v13
	v_or_b32_e32 v2, v12, v11
	v_ashrrev_i32_e32 v15, 7, v144
	v_and_or_b32 v4, v15, s0, v13
	v_lshl_or_b32 v132, v3, 10, v2
	v_lshl_or_b32 v130, v4, 10, v2
	v_bfe_u32 v182, v3, 4, 1
	v_lshlrev_b32_e32 v182, 20, v182
	v_lshrrev_b32_e32 v184, 5, v3
	v_lshlrev_b32_e32 v184, 4, v184
	v_and_b32_e32 v183, 15, v3
	v_add_u32_e32 v184, v184, v183
	v_lshl_or_b32 v182, v184, 10, v182
	v_or_b32_e32 v182, v182, v2
	v_lshlrev_b32_e32 v182, 1, v182
	v_mov_b32_e32 v183, 0
	v_add_u32_e32 v184, 0x10000, v182
	v_mov_b32_e32 v185, 0
	v_ashrrev_i32_e32 v133, 31, v132
	s_addc_u32 s9, s68, s1
	v_lshlrev_b64 v[16:17], 1, v[132:133]
	v_ashrrev_i32_e32 v131, 31, v130
	s_waitcnt lgkmcnt(0)
	s_barrier
	v_lshl_add_u64 v[2:3], s[8:9], 0, v[182:183]
	s_add_u32 m0, s32, 0x10000
	v_lshlrev_b64 v[18:19], 1, v[130:131]
	global_load_lds_dwordx4 v[2:3], off
	v_lshl_add_u64 v[6:7], s[8:9], 0, v[184:185]
	s_add_u32 m0, s32, 0x12000
	s_nop 0
	global_load_lds_dwordx4 v[6:7], off
	v_lshl_add_u64 v[8:9], s[26:27], 0, v[16:17]
	s_mov_b32 m0, s32
	s_nop 0
	global_load_lds_dwordx4 v[8:9], off
	s_add_u32 m0, s32, 0x2000
	s_add_u32 s0, s8, 0x400000
	v_lshl_add_u64 v[4:5], s[26:27], 0, v[18:19]
	s_addc_u32 s1, s9, 0
	global_load_lds_dwordx4 v[4:5], off
	v_lshl_add_u64 v[20:21], s[0:1], 0, v[182:183]
	s_add_u32 m0, s32, 0x14000
	v_add_u32_e32 v150, 0x16000, v143
	global_load_lds_dwordx4 v[20:21], off
	v_lshl_add_u64 v[20:21], s[0:1], 0, v[184:185]
	v_readfirstlane_b32 s0, v150
	v_add_u32_e32 v151, 0x4000, v143
	s_mov_b32 m0, s0
	v_readfirstlane_b32 s0, v151
	v_add_u32_e32 v152, 0x6000, v143
	global_load_lds_dwordx4 v[20:21], off
	v_lshl_add_u64 v[16:17], s[30:31], 0, v[16:17]
	s_mov_b32 m0, s0
	v_readfirstlane_b32 s0, v152
	global_load_lds_dwordx4 v[16:17], off
	v_lshl_add_u64 v[16:17], s[30:31], 0, v[18:19]
	s_mov_b32 m0, s0
	v_ashrrev_i32_e32 v14, 8, v0
	global_load_lds_dwordx4 v[16:17], off
	v_cmp_eq_u32_e32 vcc, 1, v14
	s_and_saveexec_b64 s[10:11], vcc
	s_cbranch_execz .LBB0_104
	s_barrier
.LBB0_104:
	s_or_b64 exec, exec, s[10:11]
	v_add_u32_e32 v153, 0x18000, v143
	v_add_u32_e32 v154, 0x1a000, v143
	v_readfirstlane_b32 s0, v153
	v_lshl_add_u64 v[2:3], v[2:3], 0, s[76:77]
	s_mov_b32 m0, s0
	v_readfirstlane_b32 s0, v154
	v_add_u32_e32 v155, 0x8000, v143
	s_waitcnt vmcnt(4)
	s_barrier
	global_load_lds_dwordx4 v[2:3], off
	v_lshl_add_u64 v[2:3], v[6:7], 0, s[76:77]
	s_mov_b32 m0, s0
	v_readfirstlane_b32 s0, v155
	v_add_u32_e32 v156, 0xa000, v143
	global_load_lds_dwordx4 v[2:3], off
	v_lshl_add_u64 v[2:3], v[8:9], 0, s[76:77]
	s_mov_b32 m0, s0
	v_readfirstlane_b32 s0, v156
	global_load_lds_dwordx4 v[2:3], off
	s_mov_b32 m0, s0
	s_add_u32 s0, s8, 0x400080
	v_add_u32_e32 v157, 0x1c000, v143
	v_lshl_add_u64 v[2:3], v[4:5], 0, s[76:77]
	s_addc_u32 s1, s9, 0
	v_readfirstlane_b32 s8, v157
	global_load_lds_dwordx4 v[2:3], off
	v_lshl_add_u64 v[2:3], v[182:183], 0, s[0:1]
	s_mov_b32 m0, s8
	s_nop 0
	global_load_lds_dwordx4 v[2:3], off
	v_lshl_add_u64 v[2:3], v[184:185], 0, s[0:1]
	s_add_u32 m0, s32, 0x1e000
	v_lshlrev_b32_e32 v17, 6, v0
	global_load_lds_dwordx4 v[2:3], off
	v_lshlrev_b32_e32 v2, 10, v15
	v_and_b32_e32 v2, 0xffffc000, v2
	v_lshlrev_b32_e32 v4, 10, v13
	v_lshlrev_b32_e32 v5, 10, v10
	v_and_b32_e32 v16, 48, v0
	v_and_b32_e32 v18, 0x3c0, v17
	v_lshlrev_b32_e32 v20, 2, v0
	v_or3_b32 v2, v12, v2, v4
	v_and_b32_e32 v5, 0xffffc000, v5
	v_or_b32_e32 v19, v18, v16
	v_and_b32_e32 v20, 32, v20
	s_mov_b32 s0, 0x14000
	v_add_u32_e32 v2, v2, v11
	v_or3_b32 v4, v12, v5, v4
	v_bitop3_b32 v8, v19, s0, v20 bitop3:0xde
	s_mov_b32 s0, 0x18000
	v_ashrrev_i32_e32 v3, 31, v2
	v_add_u32_e32 v4, v4, v11
	s_waitcnt vmcnt(6)
	v_bitop3_b32 v9, v19, s0, v20 bitop3:0xde
	s_mov_b32 s0, 0x1c000
	v_lshlrev_b64 v[2:3], 1, v[2:3]
	v_ashrrev_i32_e32 v5, 31, v4
	v_bitop3_b32 v16, v18, v20, v16 bitop3:0x36
	v_bitop3_b32 v6, v19, s88, v20 bitop3:0xde
	v_lshlrev_b32_e32 v7, 13, v14
	v_bitop3_b32 v14, v19, s0, v20 bitop3:0xde
	v_and_b32_e32 v17, 0x3000, v17
	v_lshl_add_u64 v[134:135], s[26:27], 0, v[2:3]
	v_lshlrev_b64 v[4:5], 1, v[4:5]
	v_lshl_add_u64 v[138:139], s[40:41], 0, v[184:185]
	v_mov_b32_e32 v2, 0
	v_lshl_add_u64 v[136:137], s[26:27], 0, v[4:5]
	v_lshl_add_u64 v[140:141], s[40:41], 0, v[182:183]
	s_mov_b32 s10, -2
	s_mov_b64 s[8:9], 0
	v_add_u32_e32 v160, v6, v17
	v_add_u32_e32 v142, v16, v7
	v_add_u32_e32 v158, v8, v17
	v_add_u32_e32 v148, v9, v17
	v_add_u32_e32 v145, v14, v17
	v_mov_b32_e32 v3, v2
	v_mov_b32_e32 v4, v2
	v_mov_b32_e32 v5, v2
	v_mov_b32_e32 v6, v2
	v_mov_b32_e32 v7, v2
	v_mov_b32_e32 v8, v2
	v_mov_b32_e32 v9, v2
	v_mov_b32_e32 v10, v2
	v_mov_b32_e32 v11, v2
	v_mov_b32_e32 v12, v2
	v_mov_b32_e32 v13, v2
	v_mov_b32_e32 v14, v2
	v_mov_b32_e32 v15, v2
	v_mov_b32_e32 v16, v2
	v_mov_b32_e32 v17, v2
	v_mov_b32_e32 v18, v2
	v_mov_b32_e32 v19, v2
	v_mov_b32_e32 v20, v2
	v_mov_b32_e32 v21, v2
	v_mov_b32_e32 v22, v2
	v_mov_b32_e32 v23, v2
	v_mov_b32_e32 v24, v2
	v_mov_b32_e32 v25, v2
	v_mov_b32_e32 v26, v2
	v_mov_b32_e32 v27, v2
	v_mov_b32_e32 v28, v2
	v_mov_b32_e32 v29, v2
	v_mov_b32_e32 v30, v2
	v_mov_b32_e32 v31, v2
	v_mov_b32_e32 v32, v2
	v_mov_b32_e32 v33, v2
	v_mov_b32_e32 v34, v2
; #define G_LDA(dst, b, h)                                                                                                  \
;   _Pragma("unroll") for (int m = 0; m < 4; ++m) _Pragma("unroll") for (int k = 0; k < 2; ++k)                             \
;       dst[m][k] = *(const bf16x8*)((const char*)G_SA(b, h) + ((wr * 4 + m) * 2 + k) * 1024 + rdo)
; #define G_LDB(dst, b, h)                                                                                                  \
;   _Pragma("unroll") for (int n = 0; n < 2; ++n) _Pragma("unroll") for (int k = 0; k < 2; ++k)                             \
;       dst[n][k] = *(const bf16x8*)((const char*)G_SB(b, h) + ((wc * 2 + n) * 2 + k) * 1024 + rdo)
; #define G_WAIT_L(n) asm volatile("s_waitcnt lgkmcnt(" #n ")" ::: "memory")
; #define G_BAR __builtin_amdgcn_s_barrier()
; #define G_SCHED __builtin_amdgcn_sched_barrier(0)
;     ...
;   for (int tt = 0; tt < nt - 2; tt += 2) {
;     G_LDB(B0, 0, 0); G_SCHED; G_LDA(At, 0, 0); G_STAGE(G_SA(1, 1), A, oa0, oa1, LDA, 128, KA(tt + 1));
;     G_WAIT_L(8); G_BAR; G_WAIT_L(0); G_MMA(0, 0, At, B0); G_BAR; G_SCHED;
;     G_LDB(B1, 0, 1); G_STAGE(G_SB(0, 0), B, ob0, ob1, LDB, 0, KB(tt + 2));
;     G_BAR; G_WAIT_L(0); G_MMA(0, 1, At, B1); G_BAR;
; DI void zero_acc256(f32x4 (&a)[2][2][4][2]) {
; #pragma unroll
;   for (int i = 0; i < 2; ++i)
; #pragma unroll
;     for (int j = 0; j < 2; ++j)
; #pragma unroll
;       for (int m = 0; m < 4; ++m)
; #pragma unroll
;         for (int n = 0; n < 2; ++n)
; #pragma unroll
;           for (int e = 0; e < 4; ++e) a[i][j][m][n][e] = 0.f;
; }
	v_mov_b32_e32 v35, v2
	v_mov_b32_e32 v36, v2
	v_mov_b32_e32 v37, v2
	v_mov_b32_e32 v38, v2
	v_mov_b32_e32 v39, v2
	v_mov_b32_e32 v40, v2
	v_mov_b32_e32 v41, v2
	v_mov_b32_e32 v42, v2
	v_mov_b32_e32 v43, v2
	v_mov_b32_e32 v44, v2
	v_mov_b32_e32 v45, v2
	v_mov_b32_e32 v46, v2
	v_mov_b32_e32 v47, v2
	v_mov_b32_e32 v48, v2
	v_mov_b32_e32 v49, v2
	v_mov_b32_e32 v50, v2
	v_mov_b32_e32 v51, v2
	v_mov_b32_e32 v52, v2
	v_mov_b32_e32 v53, v2
	v_mov_b32_e32 v54, v2
	v_mov_b32_e32 v55, v2
	v_mov_b32_e32 v56, v2
	v_mov_b32_e32 v57, v2
	v_mov_b32_e32 v58, v2
	v_mov_b32_e32 v59, v2
	v_mov_b32_e32 v60, v2
	v_mov_b32_e32 v61, v2
	v_mov_b32_e32 v62, v2
	v_mov_b32_e32 v63, v2
	v_mov_b32_e32 v64, v2
	v_mov_b32_e32 v65, v2
	v_mov_b32_e32 v66, v2
	v_mov_b32_e32 v67, v2
	v_mov_b32_e32 v68, v2
	v_mov_b32_e32 v69, v2
	v_mov_b32_e32 v70, v2
	v_mov_b32_e32 v71, v2
	v_mov_b32_e32 v72, v2
	v_mov_b32_e32 v73, v2
	v_mov_b32_e32 v74, v2
	v_mov_b32_e32 v75, v2
	v_mov_b32_e32 v76, v2
	v_mov_b32_e32 v77, v2
	v_mov_b32_e32 v78, v2
	v_mov_b32_e32 v79, v2
	v_mov_b32_e32 v80, v2
	v_mov_b32_e32 v81, v2
	v_mov_b32_e32 v82, v2
	v_mov_b32_e32 v83, v2
	v_mov_b32_e32 v84, v2
	v_mov_b32_e32 v85, v2
	v_mov_b32_e32 v86, v2
	v_mov_b32_e32 v87, v2
	v_mov_b32_e32 v88, v2
	v_mov_b32_e32 v89, v2
	v_mov_b32_e32 v90, v2
	v_mov_b32_e32 v91, v2
	v_mov_b32_e32 v92, v2
	v_mov_b32_e32 v93, v2
	v_mov_b32_e32 v94, v2
	v_mov_b32_e32 v95, v2
	v_mov_b32_e32 v96, v2
	v_mov_b32_e32 v97, v2
	v_mov_b32_e32 v98, v2
	v_mov_b32_e32 v99, v2
	v_mov_b32_e32 v100, v2
	v_mov_b32_e32 v101, v2
	v_mov_b32_e32 v102, v2
	v_mov_b32_e32 v103, v2
	v_mov_b32_e32 v104, v2
	v_mov_b32_e32 v105, v2
	v_mov_b32_e32 v106, v2
	v_mov_b32_e32 v107, v2
	v_mov_b32_e32 v108, v2
	v_mov_b32_e32 v109, v2
	v_mov_b32_e32 v110, v2
	v_mov_b32_e32 v111, v2
	v_mov_b32_e32 v112, v2
	v_mov_b32_e32 v113, v2
	v_mov_b32_e32 v114, v2
	v_mov_b32_e32 v115, v2
	v_mov_b32_e32 v116, v2
	v_mov_b32_e32 v117, v2
	v_mov_b32_e32 v118, v2
	v_mov_b32_e32 v119, v2
	v_mov_b32_e32 v120, v2
	v_mov_b32_e32 v121, v2
	v_mov_b32_e32 v122, v2
	v_mov_b32_e32 v123, v2
	v_mov_b32_e32 v124, v2
	v_mov_b32_e32 v125, v2
	v_mov_b32_e32 v126, v2
	v_mov_b32_e32 v127, v2
	v_mov_b32_e32 v128, v2
	v_mov_b32_e32 v129, v2
	s_barrier
.LBB0_105:
	ds_read_b128 v[164:167], v160
	ds_read_b128 v[182:185], v160 offset:1024
	ds_read_b128 v[186:189], v160 offset:2048
	ds_read_b128 v[190:193], v160 offset:3072
	v_lshl_add_u64 v[242:243], v[136:137], 0, s[8:9]
	v_lshl_add_u64 v[226:227], v[242:243], 0, s[78:79]
	s_add_u32 m0, s32, 0xc000
	v_lshl_add_u64 v[244:245], v[134:135], 0, s[8:9]
	ds_read_b128 v[194:197], v142
	ds_read_b128 v[198:201], v142 offset:1024
	ds_read_b128 v[202:205], v142 offset:2048
	ds_read_b128 v[206:209], v142 offset:3072
	ds_read_b128 v[210:213], v142 offset:4096
	ds_read_b128 v[214:217], v142 offset:5120
	ds_read_b128 v[218:221], v142 offset:6144
	ds_read_b128 v[222:225], v142 offset:7168
	global_load_lds_dwordx4 v[226:227], off
	s_add_u32 m0, s32, 0xe000
	v_lshl_add_u64 v[226:227], v[244:245], 0, s[78:79]
	global_load_lds_dwordx4 v[226:227], off
	s_waitcnt lgkmcnt(8)
	s_barrier
	s_waitcnt lgkmcnt(0)
	v_mfma_f32_16x16x32_bf16 v[126:129], v[194:197], v[164:167], v[126:129]
	v_mfma_f32_16x16x32_bf16 v[122:125], v[194:197], v[186:189], v[122:125]
	v_mfma_f32_16x16x32_bf16 v[118:121], v[202:205], v[164:167], v[118:121]
	v_mfma_f32_16x16x32_bf16 v[114:117], v[202:205], v[186:189], v[114:117]
	v_mfma_f32_16x16x32_bf16 v[110:113], v[210:213], v[164:167], v[110:113]
	v_mfma_f32_16x16x32_bf16 v[106:109], v[210:213], v[186:189], v[106:109]
	v_mfma_f32_16x16x32_bf16 v[102:105], v[218:221], v[164:167], v[102:105]
	v_mfma_f32_16x16x32_bf16 v[98:101], v[218:221], v[186:189], v[98:101]
	v_mfma_f32_16x16x32_bf16 v[126:129], v[198:201], v[182:185], v[126:129]
	v_mfma_f32_16x16x32_bf16 v[122:125], v[198:201], v[190:193], v[122:125]
	v_mfma_f32_16x16x32_bf16 v[118:121], v[206:209], v[182:185], v[118:121]
	v_mfma_f32_16x16x32_bf16 v[114:117], v[206:209], v[190:193], v[114:117]
	v_mfma_f32_16x16x32_bf16 v[110:113], v[214:217], v[182:185], v[110:113]
	v_mfma_f32_16x16x32_bf16 v[106:109], v[214:217], v[190:193], v[106:109]
	v_mfma_f32_16x16x32_bf16 v[102:105], v[222:225], v[182:185], v[102:105]
	v_mfma_f32_16x16x32_bf16 v[98:101], v[222:225], v[190:193], v[98:101]
	s_barrier
	v_lshl_add_u64 v[246:247], v[140:141], 0, s[8:9]
	v_lshl_add_u64 v[248:249], v[246:247], 0, s[50:51]
	s_add_u32 m0, s32, 0x10000
	ds_read_b128 v[226:229], v158
	ds_read_b128 v[230:233], v158 offset:1024
	ds_read_b128 v[234:237], v158 offset:2048
	ds_read_b128 v[238:241], v158 offset:3072
	global_load_lds_dwordx4 v[248:249], off
	v_lshl_add_u64 v[248:249], v[138:139], 0, s[8:9]
	s_add_u32 m0, s32, 0x12000
	v_lshl_add_u64 v[250:251], v[248:249], 0, s[50:51]
	global_load_lds_dwordx4 v[250:251], off
	s_barrier
	s_waitcnt lgkmcnt(0)
	v_mfma_f32_16x16x32_bf16 v[94:97], v[194:197], v[226:229], v[94:97]
	v_mfma_f32_16x16x32_bf16 v[90:93], v[194:197], v[234:237], v[90:93]
	v_mfma_f32_16x16x32_bf16 v[86:89], v[202:205], v[226:229], v[86:89]
	v_mfma_f32_16x16x32_bf16 v[82:85], v[202:205], v[234:237], v[82:85]
	v_mfma_f32_16x16x32_bf16 v[78:81], v[210:213], v[226:229], v[78:81]
	v_mfma_f32_16x16x32_bf16 v[74:77], v[210:213], v[234:237], v[74:77]
	v_mfma_f32_16x16x32_bf16 v[70:73], v[218:221], v[226:229], v[70:73]
	v_mfma_f32_16x16x32_bf16 v[66:69], v[218:221], v[234:237], v[66:69]
	v_mfma_f32_16x16x32_bf16 v[94:97], v[198:201], v[230:233], v[94:97]
	v_mfma_f32_16x16x32_bf16 v[90:93], v[198:201], v[238:241], v[90:93]
	v_mfma_f32_16x16x32_bf16 v[86:89], v[206:209], v[230:233], v[86:89]
	v_mfma_f32_16x16x32_bf16 v[82:85], v[206:209], v[238:241], v[82:85]
	v_mfma_f32_16x16x32_bf16 v[78:81], v[214:217], v[230:233], v[78:81]
	v_mfma_f32_16x16x32_bf16 v[74:77], v[214:217], v[238:241], v[74:77]
	v_mfma_f32_16x16x32_bf16 v[70:73], v[222:225], v[230:233], v[70:73]
	v_mfma_f32_16x16x32_bf16 v[66:69], v[222:225], v[238:241], v[66:69]
	v_lshl_add_u64 v[250:251], v[242:243], 0, s[82:83]
	s_mov_b32 m0, s32
	s_barrier
; #define G_LDA(dst, b, h)                                                                                                  \
;   _Pragma("unroll") for (int m = 0; m < 4; ++m) _Pragma("unroll") for (int k = 0; k < 2; ++k)                             \
;       dst[m][k] = *(const bf16x8*)((const char*)G_SA(b, h) + ((wr * 4 + m) * 2 + k) * 1024 + rdo)
; #define G_LDB(dst, b, h)                                                                                                  \
;   _Pragma("unroll") for (int n = 0; n < 2; ++n) _Pragma("unroll") for (int k = 0; k < 2; ++k)                             \
;       dst[n][k] = *(const bf16x8*)((const char*)G_SB(b, h) + ((wc * 2 + n) * 2 + k) * 1024 + rdo)
; #define G_WAIT_V(n) asm volatile("s_waitcnt vmcnt(" #n ")" ::: "memory")
; #define G_WAIT_L(n) asm volatile("s_waitcnt lgkmcnt(" #n ")" ::: "memory")
; #define G_BAR __builtin_amdgcn_s_barrier()
; #define G_SCHED __builtin_amdgcn_sched_barrier(0)
;     ...
;     G_BAR; G_WAIT_L(0); G_MMA(0, 1, At, B1); G_BAR;
;     G_LDA(At, 0, 1); G_STAGE(G_SA(0, 0), A, oa0, oa1, LDA, 0, KA(tt + 2));
;     G_BAR; G_WAIT_L(0); G_MMA(1, 0, At, B0); G_BAR; G_SCHED;
;     G_STAGE(G_SB(0, 1), B, ob0, ob1, LDB, 128, KB(tt + 2));
;     G_WAIT_V(6); G_BAR; G_MMA(1, 1, At, B1); G_BAR;
;     G_LDB(B0, 1, 0); G_SCHED; G_LDA(At, 1, 0); G_STAGE(G_SA(0, 1), A, oa0, oa1, LDA, 128, KA(tt + 2));
;     G_WAIT_L(8); G_BAR; G_WAIT_L(0); G_MMA(0, 0, At, B0); G_BAR; G_SCHED;
;     G_LDB(B1, 1, 1); G_STAGE(G_SB(1, 0), B, ob0, ob1, LDB, 0, KB(tt + 3));
;     G_BAR; G_WAIT_L(0); G_MMA(0, 1, At, B1); G_BAR;
	ds_read_b128 v[194:197], v142 offset:16384
	ds_read_b128 v[198:201], v142 offset:17408
	ds_read_b128 v[202:205], v142 offset:18432
	ds_read_b128 v[206:209], v142 offset:19456
	ds_read_b128 v[210:213], v142 offset:20480
	ds_read_b128 v[214:217], v142 offset:21504
	ds_read_b128 v[218:221], v142 offset:22528
	ds_read_b128 v[222:225], v142 offset:23552
	global_load_lds_dwordx4 v[250:251], off
	s_add_u32 m0, s32, 0x2000
	v_lshl_add_u64 v[250:251], v[244:245], 0, s[82:83]
	global_load_lds_dwordx4 v[250:251], off
	s_barrier
	s_waitcnt lgkmcnt(0)
	v_mfma_f32_16x16x32_bf16 v[62:65], v[194:197], v[164:167], v[62:65]
	v_mfma_f32_16x16x32_bf16 v[58:61], v[194:197], v[186:189], v[58:61]
	v_mfma_f32_16x16x32_bf16 v[54:57], v[202:205], v[164:167], v[54:57]
	v_mfma_f32_16x16x32_bf16 v[50:53], v[202:205], v[186:189], v[50:53]
	v_mfma_f32_16x16x32_bf16 v[46:49], v[210:213], v[164:167], v[46:49]
	v_mfma_f32_16x16x32_bf16 v[42:45], v[210:213], v[186:189], v[42:45]
	v_mfma_f32_16x16x32_bf16 v[38:41], v[218:221], v[164:167], v[38:41]
	v_mfma_f32_16x16x32_bf16 v[34:37], v[218:221], v[186:189], v[34:37]
	v_mfma_f32_16x16x32_bf16 v[62:65], v[198:201], v[182:185], v[62:65]
	v_mfma_f32_16x16x32_bf16 v[58:61], v[198:201], v[190:193], v[58:61]
	v_mfma_f32_16x16x32_bf16 v[54:57], v[206:209], v[182:185], v[54:57]
	v_mfma_f32_16x16x32_bf16 v[50:53], v[206:209], v[190:193], v[50:53]
	v_mfma_f32_16x16x32_bf16 v[46:49], v[214:217], v[182:185], v[46:49]
	v_mfma_f32_16x16x32_bf16 v[42:45], v[214:217], v[190:193], v[42:45]
	v_mfma_f32_16x16x32_bf16 v[38:41], v[222:225], v[182:185], v[38:41]
	v_mfma_f32_16x16x32_bf16 v[34:37], v[222:225], v[190:193], v[34:37]
	s_barrier
	v_lshl_add_u64 v[164:165], v[246:247], 0, s[38:39]
	s_add_u32 m0, s32, 0x14000
	v_readfirstlane_b32 s0, v150
	global_load_lds_dwordx4 v[164:165], off
	s_mov_b32 m0, s0
	v_lshl_add_u64 v[164:165], v[248:249], 0, s[38:39]
	global_load_lds_dwordx4 v[164:165], off
	s_waitcnt vmcnt(6)
	s_barrier
	v_mfma_f32_16x16x32_bf16 v[30:33], v[194:197], v[226:229], v[30:33]
	v_mfma_f32_16x16x32_bf16 v[26:29], v[194:197], v[234:237], v[26:29]
	v_mfma_f32_16x16x32_bf16 v[22:25], v[202:205], v[226:229], v[22:25]
	v_mfma_f32_16x16x32_bf16 v[18:21], v[202:205], v[234:237], v[18:21]
	v_mfma_f32_16x16x32_bf16 v[14:17], v[210:213], v[226:229], v[14:17]
	v_mfma_f32_16x16x32_bf16 v[10:13], v[210:213], v[234:237], v[10:13]
	v_mfma_f32_16x16x32_bf16 v[6:9], v[218:221], v[226:229], v[6:9]
	v_mfma_f32_16x16x32_bf16 v[2:5], v[218:221], v[234:237], v[2:5]
	v_mfma_f32_16x16x32_bf16 v[30:33], v[198:201], v[230:233], v[30:33]
	v_mfma_f32_16x16x32_bf16 v[26:29], v[198:201], v[238:241], v[26:29]
	v_mfma_f32_16x16x32_bf16 v[22:25], v[206:209], v[230:233], v[22:25]
	v_mfma_f32_16x16x32_bf16 v[18:21], v[206:209], v[238:241], v[18:21]
	v_mfma_f32_16x16x32_bf16 v[14:17], v[214:217], v[230:233], v[14:17]
	v_mfma_f32_16x16x32_bf16 v[10:13], v[214:217], v[238:241], v[10:13]
	v_mfma_f32_16x16x32_bf16 v[6:9], v[222:225], v[230:233], v[6:9]
	v_mfma_f32_16x16x32_bf16 v[2:5], v[222:225], v[238:241], v[2:5]
	s_barrier
	ds_read_b128 v[164:167], v148
	ds_read_b128 v[182:185], v148 offset:1024
	ds_read_b128 v[186:189], v148 offset:2048
	ds_read_b128 v[190:193], v148 offset:3072
	v_readfirstlane_b32 s0, v151
	v_lshl_add_u64 v[226:227], v[242:243], 0, s[86:87]
	s_mov_b32 m0, s0
	v_readfirstlane_b32 s0, v152
	ds_read_b128 v[194:197], v142 offset:32768
	ds_read_b128 v[198:201], v142 offset:33792
	ds_read_b128 v[202:205], v142 offset:34816
	ds_read_b128 v[206:209], v142 offset:35840
	ds_read_b128 v[210:213], v142 offset:36864
	ds_read_b128 v[214:217], v142 offset:37888
	ds_read_b128 v[218:221], v142 offset:38912
	ds_read_b128 v[222:225], v142 offset:39936
	global_load_lds_dwordx4 v[226:227], off
	s_mov_b32 m0, s0
	v_lshl_add_u64 v[226:227], v[244:245], 0, s[86:87]
	global_load_lds_dwordx4 v[226:227], off
	s_waitcnt lgkmcnt(8)
	s_barrier
	s_waitcnt lgkmcnt(0)
	v_mfma_f32_16x16x32_bf16 v[126:129], v[194:197], v[164:167], v[126:129]
	v_mfma_f32_16x16x32_bf16 v[122:125], v[194:197], v[186:189], v[122:125]
	v_mfma_f32_16x16x32_bf16 v[118:121], v[202:205], v[164:167], v[118:121]
	v_mfma_f32_16x16x32_bf16 v[114:117], v[202:205], v[186:189], v[114:117]
	v_mfma_f32_16x16x32_bf16 v[110:113], v[210:213], v[164:167], v[110:113]
	v_mfma_f32_16x16x32_bf16 v[106:109], v[210:213], v[186:189], v[106:109]
	v_mfma_f32_16x16x32_bf16 v[102:105], v[218:221], v[164:167], v[102:105]
	v_mfma_f32_16x16x32_bf16 v[98:101], v[218:221], v[186:189], v[98:101]
	v_mfma_f32_16x16x32_bf16 v[126:129], v[198:201], v[182:185], v[126:129]
	v_mfma_f32_16x16x32_bf16 v[122:125], v[198:201], v[190:193], v[122:125]
	v_mfma_f32_16x16x32_bf16 v[118:121], v[206:209], v[182:185], v[118:121]
	v_mfma_f32_16x16x32_bf16 v[114:117], v[206:209], v[190:193], v[114:117]
	v_mfma_f32_16x16x32_bf16 v[110:113], v[214:217], v[182:185], v[110:113]
	v_mfma_f32_16x16x32_bf16 v[106:109], v[214:217], v[190:193], v[106:109]
	v_mfma_f32_16x16x32_bf16 v[102:105], v[222:225], v[182:185], v[102:105]
	v_mfma_f32_16x16x32_bf16 v[98:101], v[222:225], v[190:193], v[98:101]
	s_barrier
	v_readfirstlane_b32 s0, v153
	v_lshl_add_u64 v[250:251], v[246:247], 0, s[4:5]
	s_mov_b32 m0, s0
	v_readfirstlane_b32 s0, v154
	ds_read_b128 v[226:229], v145
	ds_read_b128 v[230:233], v145 offset:1024
	ds_read_b128 v[234:237], v145 offset:2048
	ds_read_b128 v[238:241], v145 offset:3072
	global_load_lds_dwordx4 v[250:251], off
	s_mov_b32 m0, s0
	v_lshl_add_u64 v[250:251], v[248:249], 0, s[4:5]
	global_load_lds_dwordx4 v[250:251], off
	s_barrier
; #define G_LDA(dst, b, h)                                                                                                  \
;   _Pragma("unroll") for (int m = 0; m < 4; ++m) _Pragma("unroll") for (int k = 0; k < 2; ++k)                             \
;       dst[m][k] = *(const bf16x8*)((const char*)G_SA(b, h) + ((wr * 4 + m) * 2 + k) * 1024 + rdo)
; #define G_LDB(dst, b, h)                                                                                                  \
;   _Pragma("unroll") for (int n = 0; n < 2; ++n) _Pragma("unroll") for (int k = 0; k < 2; ++k)                             \
;       dst[n][k] = *(const bf16x8*)((const char*)G_SB(b, h) + ((wc * 2 + n) * 2 + k) * 1024 + rdo)
; #define G_WAIT_V(n) asm volatile("s_waitcnt vmcnt(" #n ")" ::: "memory")
; #define G_WAIT_L(n) asm volatile("s_waitcnt lgkmcnt(" #n ")" ::: "memory")
; #define G_BAR __builtin_amdgcn_s_barrier()
; #define G_SCHED __builtin_amdgcn_sched_barrier(0)
; DI void br_flush(PREF p, f32x4 (&acc)[2][2][4][2], int slot) { br_store(p, acc, slot); zero_acc256(acc); }
;     ...
;     G_LDB(B1, 1, 1); G_STAGE(G_SB(1, 0), B, ob0, ob1, LDB, 0, KB(tt + 3));
;     G_BAR; G_WAIT_L(0); G_MMA(0, 1, At, B1); G_BAR;
;     G_LDA(At, 1, 1); G_STAGE(G_SA(1, 0), A, oa0, oa1, LDA, 0, KA(tt + 3));
;     G_BAR; G_WAIT_L(0); G_MMA(1, 0, At, B0); G_BAR; G_SCHED;
;     G_STAGE(G_SB(1, 1), B, ob0, ob1, LDB, 128, KB(tt + 3));
;     G_WAIT_V(6); G_BAR; G_MMA(1, 1, At, B1); G_BAR;
;     if (MODE && ((tt + 1) & 3) == 3) br_flush(p, acc, (tt + 1) >> 2);
;   }
;   {
;     G_LDB(B0, 0, 0); G_LDA(At, 0, 0); G_STAGE(G_SA(1, 1), A, oa0, oa1, LDA, 128, KA(nt - 1));
	s_waitcnt lgkmcnt(0)
	v_mfma_f32_16x16x32_bf16 v[94:97], v[194:197], v[226:229], v[94:97]
	v_mfma_f32_16x16x32_bf16 v[90:93], v[194:197], v[234:237], v[90:93]
	v_mfma_f32_16x16x32_bf16 v[86:89], v[202:205], v[226:229], v[86:89]
	v_mfma_f32_16x16x32_bf16 v[82:85], v[202:205], v[234:237], v[82:85]
	v_mfma_f32_16x16x32_bf16 v[78:81], v[210:213], v[226:229], v[78:81]
	v_mfma_f32_16x16x32_bf16 v[74:77], v[210:213], v[234:237], v[74:77]
	v_mfma_f32_16x16x32_bf16 v[70:73], v[218:221], v[226:229], v[70:73]
	v_mfma_f32_16x16x32_bf16 v[66:69], v[218:221], v[234:237], v[66:69]
	v_mfma_f32_16x16x32_bf16 v[94:97], v[198:201], v[230:233], v[94:97]
	v_mfma_f32_16x16x32_bf16 v[90:93], v[198:201], v[238:241], v[90:93]
	v_mfma_f32_16x16x32_bf16 v[86:89], v[206:209], v[230:233], v[86:89]
	v_mfma_f32_16x16x32_bf16 v[82:85], v[206:209], v[238:241], v[82:85]
	v_mfma_f32_16x16x32_bf16 v[78:81], v[214:217], v[230:233], v[78:81]
	v_mfma_f32_16x16x32_bf16 v[74:77], v[214:217], v[238:241], v[74:77]
	v_mfma_f32_16x16x32_bf16 v[70:73], v[222:225], v[230:233], v[70:73]
	v_mfma_f32_16x16x32_bf16 v[66:69], v[222:225], v[238:241], v[66:69]
	v_readfirstlane_b32 s0, v155
	v_lshl_add_u64 v[242:243], v[242:243], 0, s[90:91]
	s_mov_b32 m0, s0
	v_readfirstlane_b32 s0, v156
	s_barrier
	ds_read_b128 v[194:197], v142 offset:49152
	ds_read_b128 v[198:201], v142 offset:50176
	ds_read_b128 v[202:205], v142 offset:51200
	ds_read_b128 v[206:209], v142 offset:52224
	ds_read_b128 v[210:213], v142 offset:53248
	ds_read_b128 v[214:217], v142 offset:54272
	ds_read_b128 v[218:221], v142 offset:55296
	ds_read_b128 v[222:225], v142 offset:56320
	global_load_lds_dwordx4 v[242:243], off
	s_mov_b32 m0, s0
	v_lshl_add_u64 v[242:243], v[244:245], 0, s[90:91]
	global_load_lds_dwordx4 v[242:243], off
	s_barrier
	s_waitcnt lgkmcnt(0)
	v_mfma_f32_16x16x32_bf16 v[62:65], v[194:197], v[164:167], v[62:65]
	v_mfma_f32_16x16x32_bf16 v[58:61], v[194:197], v[186:189], v[58:61]
	v_mfma_f32_16x16x32_bf16 v[54:57], v[202:205], v[164:167], v[54:57]
	v_mfma_f32_16x16x32_bf16 v[50:53], v[202:205], v[186:189], v[50:53]
	v_mfma_f32_16x16x32_bf16 v[46:49], v[210:213], v[164:167], v[46:49]
	v_mfma_f32_16x16x32_bf16 v[42:45], v[210:213], v[186:189], v[42:45]
	v_mfma_f32_16x16x32_bf16 v[38:41], v[218:221], v[164:167], v[38:41]
	v_mfma_f32_16x16x32_bf16 v[34:37], v[218:221], v[186:189], v[34:37]
	v_mfma_f32_16x16x32_bf16 v[62:65], v[198:201], v[182:185], v[62:65]
	v_mfma_f32_16x16x32_bf16 v[58:61], v[198:201], v[190:193], v[58:61]
	v_mfma_f32_16x16x32_bf16 v[54:57], v[206:209], v[182:185], v[54:57]
	v_mfma_f32_16x16x32_bf16 v[50:53], v[206:209], v[190:193], v[50:53]
	v_mfma_f32_16x16x32_bf16 v[46:49], v[214:217], v[182:185], v[46:49]
	v_mfma_f32_16x16x32_bf16 v[42:45], v[214:217], v[190:193], v[42:45]
	v_mfma_f32_16x16x32_bf16 v[38:41], v[222:225], v[182:185], v[38:41]
	v_mfma_f32_16x16x32_bf16 v[34:37], v[222:225], v[190:193], v[34:37]
	s_barrier
	v_readfirstlane_b32 s0, v157
	v_lshl_add_u64 v[164:165], v[246:247], 0, s[74:75]
	s_mov_b32 m0, s0
	s_nop 0
	global_load_lds_dwordx4 v[164:165], off
	s_add_u32 m0, s32, 0x1e000
	v_lshl_add_u64 v[164:165], v[248:249], 0, s[74:75]
	global_load_lds_dwordx4 v[164:165], off
	s_waitcnt vmcnt(6)
	s_barrier
	v_mfma_f32_16x16x32_bf16 v[30:33], v[194:197], v[226:229], v[30:33]
	v_mfma_f32_16x16x32_bf16 v[26:29], v[194:197], v[234:237], v[26:29]
	v_mfma_f32_16x16x32_bf16 v[22:25], v[202:205], v[226:229], v[22:25]
	v_mfma_f32_16x16x32_bf16 v[18:21], v[202:205], v[234:237], v[18:21]
	v_mfma_f32_16x16x32_bf16 v[14:17], v[210:213], v[226:229], v[14:17]
	v_mfma_f32_16x16x32_bf16 v[10:13], v[210:213], v[234:237], v[10:13]
	v_mfma_f32_16x16x32_bf16 v[6:9], v[218:221], v[226:229], v[6:9]
	v_mfma_f32_16x16x32_bf16 v[2:5], v[218:221], v[234:237], v[2:5]
	v_mfma_f32_16x16x32_bf16 v[30:33], v[198:201], v[230:233], v[30:33]
	v_mfma_f32_16x16x32_bf16 v[26:29], v[198:201], v[238:241], v[26:29]
	v_mfma_f32_16x16x32_bf16 v[22:25], v[206:209], v[230:233], v[22:25]
	v_mfma_f32_16x16x32_bf16 v[18:21], v[206:209], v[238:241], v[18:21]
	v_mfma_f32_16x16x32_bf16 v[14:17], v[214:217], v[230:233], v[14:17]
	v_mfma_f32_16x16x32_bf16 v[10:13], v[214:217], v[238:241], v[10:13]
	v_mfma_f32_16x16x32_bf16 v[6:9], v[222:225], v[230:233], v[6:9]
	v_mfma_f32_16x16x32_bf16 v[2:5], v[222:225], v[238:241], v[2:5]
	s_add_i32 s10, s10, 2
	s_add_u32 s8, s8, 0x100
	s_addc_u32 s9, s9, 0
	s_cmp_lt_u32 s10, 12
	s_barrier
	s_cbranch_scc1 .LBB0_105
	v_lshl_add_u64 v[132:133], v[132:133], 1, s[34:35]
	s_add_u32 m0, s32, 0xc000
	ds_read_b128 v[134:137], v160
	ds_read_b128 v[138:141], v160 offset:1024
	ds_read_b128 v[150:153], v160 offset:2048
	ds_read_b128 v[154:157], v160 offset:3072
	ds_read_b128 v[164:167], v142
	ds_read_b128 v[182:185], v142 offset:1024
	ds_read_b128 v[186:189], v142 offset:2048
	ds_read_b128 v[190:193], v142 offset:3072
	ds_read_b128 v[194:197], v142 offset:4096
	ds_read_b128 v[198:201], v142 offset:5120
	ds_read_b128 v[202:205], v142 offset:6144
	ds_read_b128 v[206:209], v142 offset:7168
	global_load_lds_dwordx4 v[132:133], off
	s_add_u32 m0, s32, 0xe000
	v_lshl_add_u64 v[130:131], v[130:131], 1, s[34:35]
	global_load_lds_dwordx4 v[130:131], off
	s_lshl_b32 s1, s23, 8
	s_add_u32 s98, s25, s1
	s_addc_u32 s99, s48, 0
	v_bfe_u32 v251, v168, 6, 2
	v_lshlrev_b32_e32 v248, 6, v251
	v_and_b32_e32 v250, 15, v168
	v_lshl_or_b32 v248, v250, 2, v248
	global_load_dword v170, v248, s[98:99]
	s_add_u32 s98, s98, 0x1000
	s_addc_u32 s99, s99, 0
	global_load_dword v252, v248, s[98:99]
	s_add_u32 s98, s98, 0x1000
	s_addc_u32 s99, s99, 0
	global_load_dword v253, v248, s[98:99]
	s_add_u32 s98, s98, 0x1000
	s_addc_u32 s99, s99, 0
	global_load_dword v162, v248, s[98:99]
	s_lshl_b32 s1, s23, 1
	v_lshrrev_b32_e32 v249, 1, v251
	v_add_u32_e32 v249, s1, v249
	v_and_b32_e32 v249, 3, v249
	v_lshrrev_b32_e32 v250, 8, v168
	v_lshl_add_u32 v249, v250, 2, v249
	v_lshlrev_b32_e32 v249, 14, v249
	v_and_b32_e32 v250, 63, v168
	v_lshl_or_b32 v249, v250, 4, v249
	v_and_b32_e32 v250, 1, v251
	v_lshl_or_b32 v249, v250, 3, v249
	s_lshr_b32 s1, s23, 1
	s_lshl_b32 s1, s1, 12
	s_add_u32 s20, s63, s1
	s_addc_u32 s21, s64, 0
	global_load_dwordx2 v[230:231], v249, s[20:21] offset:0
	global_load_dwordx2 v[238:239], v249, s[20:21] offset:1024
	s_add_u32 s20, s20, 0x20000
	s_addc_u32 s21, s21, 0
	global_load_dwordx2 v[232:233], v249, s[20:21] offset:0
	global_load_dwordx2 v[240:241], v249, s[20:21] offset:1024
	s_add_u32 s20, s20, 0x20000
	s_addc_u32 s21, s21, 0
	global_load_dwordx2 v[234:235], v249, s[20:21] offset:0
	global_load_dwordx2 v[242:243], v249, s[20:21] offset:1024
	s_add_u32 s20, s20, 0x20000
	s_addc_u32 s21, s21, 0
	global_load_dwordx2 v[236:237], v249, s[20:21] offset:0
	global_load_dwordx2 v[244:245], v249, s[20:21] offset:1024
	s_barrier
; #define G_LDA(dst, b, h)                                                                                                  \
;   _Pragma("unroll") for (int m = 0; m < 4; ++m) _Pragma("unroll") for (int k = 0; k < 2; ++k)                             \
;       dst[m][k] = *(const bf16x8*)((const char*)G_SA(b, h) + ((wr * 4 + m) * 2 + k) * 1024 + rdo)
; #define G_LDB(dst, b, h)                                                                                                  \
;   _Pragma("unroll") for (int n = 0; n < 2; ++n) _Pragma("unroll") for (int k = 0; k < 2; ++k)                             \
;       dst[n][k] = *(const bf16x8*)((const char*)G_SB(b, h) + ((wc * 2 + n) * 2 + k) * 1024 + rdo)
; #define G_WAIT_V(n) asm volatile("s_waitcnt vmcnt(" #n ")" ::: "memory")
; #define G_WAIT_L(n) asm volatile("s_waitcnt lgkmcnt(" #n ")" ::: "memory")
; #define G_BAR __builtin_amdgcn_s_barrier()
;     ...
;     G_LDB(B0, 0, 0); G_LDA(At, 0, 0); G_STAGE(G_SA(1, 1), A, oa0, oa1, LDA, 128, KA(nt - 1));
;     G_BAR; G_WAIT_L(0); G_MMA(0, 0, At, B0); G_BAR;
;     G_LDB(B1, 0, 1); G_BAR; G_WAIT_L(0); G_MMA(0, 1, At, B1); G_BAR;
;     G_LDA(At, 0, 1); G_WAIT_V(4); G_BAR; G_WAIT_L(0); G_MMA(1, 0, At, B0); G_MMA(1, 1, At, B1); G_BAR;
	s_waitcnt lgkmcnt(0)
	v_mfma_f32_16x16x32_bf16 v[126:129], v[164:167], v[134:137], v[126:129]
	v_mfma_f32_16x16x32_bf16 v[122:125], v[164:167], v[150:153], v[122:125]
	v_mfma_f32_16x16x32_bf16 v[114:117], v[186:189], v[150:153], v[114:117]
	v_mfma_f32_16x16x32_bf16 v[110:113], v[194:197], v[134:137], v[110:113]
	v_mfma_f32_16x16x32_bf16 v[106:109], v[194:197], v[150:153], v[106:109]
	v_mfma_f32_16x16x32_bf16 v[102:105], v[202:205], v[134:137], v[102:105]
	v_mfma_f32_16x16x32_bf16 v[98:101], v[202:205], v[150:153], v[98:101]
	v_mfma_f32_16x16x32_bf16 v[126:129], v[182:185], v[138:141], v[126:129]
	v_mfma_f32_16x16x32_bf16 v[122:125], v[182:185], v[154:157], v[122:125]
	v_mfma_f32_16x16x32_bf16 v[118:121], v[186:189], v[134:137], v[118:121]
	v_mfma_f32_16x16x32_bf16 v[114:117], v[190:193], v[154:157], v[114:117]
	v_mfma_f32_16x16x32_bf16 v[110:113], v[198:201], v[138:141], v[110:113]
	v_mfma_f32_16x16x32_bf16 v[106:109], v[198:201], v[154:157], v[106:109]
	v_mfma_f32_16x16x32_bf16 v[102:105], v[206:209], v[138:141], v[102:105]
	v_mfma_f32_16x16x32_bf16 v[98:101], v[206:209], v[154:157], v[98:101]
	v_mfma_f32_16x16x32_bf16 v[118:121], v[190:193], v[138:141], v[118:121]
	s_barrier
	ds_read_b128 v[130:133], v158
	ds_read_b128 v[210:213], v158 offset:1024
	ds_read_b128 v[214:217], v158 offset:2048
	ds_read_b128 v[158:161], v158 offset:3072
	s_barrier
	s_waitcnt lgkmcnt(0)
	v_mfma_f32_16x16x32_bf16 v[94:97], v[164:167], v[130:133], v[94:97]
	v_mfma_f32_16x16x32_bf16 v[90:93], v[164:167], v[214:217], v[90:93]
	v_mfma_f32_16x16x32_bf16 v[86:89], v[186:189], v[130:133], v[86:89]
	v_mfma_f32_16x16x32_bf16 v[82:85], v[186:189], v[214:217], v[82:85]
	v_mfma_f32_16x16x32_bf16 v[78:81], v[194:197], v[130:133], v[78:81]
	v_mfma_f32_16x16x32_bf16 v[74:77], v[194:197], v[214:217], v[74:77]
	v_mfma_f32_16x16x32_bf16 v[70:73], v[202:205], v[130:133], v[70:73]
	v_mfma_f32_16x16x32_bf16 v[66:69], v[202:205], v[214:217], v[66:69]
	v_mfma_f32_16x16x32_bf16 v[94:97], v[182:185], v[210:213], v[94:97]
	v_mfma_f32_16x16x32_bf16 v[90:93], v[182:185], v[158:161], v[90:93]
	v_mfma_f32_16x16x32_bf16 v[86:89], v[190:193], v[210:213], v[86:89]
	v_mfma_f32_16x16x32_bf16 v[82:85], v[190:193], v[158:161], v[82:85]
	v_mfma_f32_16x16x32_bf16 v[78:81], v[198:201], v[210:213], v[78:81]
	v_mfma_f32_16x16x32_bf16 v[74:77], v[198:201], v[158:161], v[74:77]
	v_mfma_f32_16x16x32_bf16 v[70:73], v[206:209], v[210:213], v[70:73]
	v_mfma_f32_16x16x32_bf16 v[66:69], v[206:209], v[158:161], v[66:69]
	s_barrier
	ds_read_b128 v[164:167], v142 offset:16384
	ds_read_b128 v[182:185], v142 offset:17408
	ds_read_b128 v[186:189], v142 offset:18432
	ds_read_b128 v[190:193], v142 offset:19456
	ds_read_b128 v[194:197], v142 offset:20480
	ds_read_b128 v[198:201], v142 offset:21504
	ds_read_b128 v[202:205], v142 offset:22528
	ds_read_b128 v[206:209], v142 offset:23552
	s_waitcnt vmcnt(16)
	s_barrier
	s_waitcnt lgkmcnt(0)
	v_mfma_f32_16x16x32_bf16 v[62:65], v[164:167], v[134:137], v[62:65]
	v_mfma_f32_16x16x32_bf16 v[58:61], v[164:167], v[150:153], v[58:61]
	v_mfma_f32_16x16x32_bf16 v[54:57], v[186:189], v[134:137], v[54:57]
	v_mfma_f32_16x16x32_bf16 v[50:53], v[186:189], v[150:153], v[50:53]
	v_mfma_f32_16x16x32_bf16 v[46:49], v[194:197], v[134:137], v[46:49]
	v_mfma_f32_16x16x32_bf16 v[38:41], v[202:205], v[134:137], v[38:41]
	v_mfma_f32_16x16x32_bf16 v[34:37], v[202:205], v[150:153], v[34:37]
	v_mfma_f32_16x16x32_bf16 v[62:65], v[182:185], v[138:141], v[62:65]
	v_mfma_f32_16x16x32_bf16 v[58:61], v[182:185], v[154:157], v[58:61]
	v_mfma_f32_16x16x32_bf16 v[54:57], v[190:193], v[138:141], v[54:57]
	v_mfma_f32_16x16x32_bf16 v[50:53], v[190:193], v[154:157], v[50:53]
	v_mfma_f32_16x16x32_bf16 v[46:49], v[198:201], v[138:141], v[46:49]
	v_mfma_f32_16x16x32_bf16 v[42:45], v[194:197], v[150:153], v[42:45]
	v_mfma_f32_16x16x32_bf16 v[38:41], v[206:209], v[138:141], v[38:41]
	v_mfma_f32_16x16x32_bf16 v[34:37], v[206:209], v[154:157], v[34:37]
	v_mfma_f32_16x16x32_bf16 v[42:45], v[198:201], v[154:157], v[42:45]
	v_mfma_f32_16x16x32_bf16 v[26:29], v[164:167], v[214:217], v[26:29]
	v_mfma_f32_16x16x32_bf16 v[22:25], v[186:189], v[130:133], v[22:25]
	v_mfma_f32_16x16x32_bf16 v[14:17], v[194:197], v[130:133], v[14:17]
	v_mfma_f32_16x16x32_bf16 v[10:13], v[194:197], v[214:217], v[10:13]
	v_mfma_f32_16x16x32_bf16 v[2:5], v[202:205], v[214:217], v[2:5]
	v_mfma_f32_16x16x32_bf16 v[30:33], v[164:167], v[130:133], v[30:33]
	v_mfma_f32_16x16x32_bf16 v[26:29], v[182:185], v[158:161], v[26:29]
	v_mfma_f32_16x16x32_bf16 v[22:25], v[190:193], v[210:213], v[22:25]
	v_mfma_f32_16x16x32_bf16 v[18:21], v[186:189], v[214:217], v[18:21]
	v_mfma_f32_16x16x32_bf16 v[14:17], v[198:201], v[210:213], v[14:17]
	v_mfma_f32_16x16x32_bf16 v[10:13], v[198:201], v[158:161], v[10:13]
	v_mfma_f32_16x16x32_bf16 v[6:9], v[202:205], v[130:133], v[6:9]
	v_mfma_f32_16x16x32_bf16 v[2:5], v[206:209], v[158:161], v[2:5]
	v_mfma_f32_16x16x32_bf16 v[30:33], v[182:185], v[210:213], v[30:33]
	v_mfma_f32_16x16x32_bf16 v[18:21], v[190:193], v[158:161], v[18:21]
	v_mfma_f32_16x16x32_bf16 v[6:9], v[206:209], v[210:213], v[6:9]
	s_barrier
	ds_read_b128 v[130:133], v148
	ds_read_b128 v[154:157], v148 offset:1024
	ds_read_b128 v[164:167], v148 offset:2048
	ds_read_b128 v[182:185], v148 offset:3072
	ds_read_b128 v[186:189], v142 offset:32768
	ds_read_b128 v[190:193], v142 offset:33792
	ds_read_b128 v[194:197], v142 offset:34816
	ds_read_b128 v[198:201], v142 offset:35840
	ds_read_b128 v[202:205], v142 offset:36864
	ds_read_b128 v[206:209], v142 offset:37888
	ds_read_b128 v[210:213], v142 offset:38912
	ds_read_b128 v[214:217], v142 offset:39936
	s_waitcnt vmcnt(14)
	s_barrier
; #define G_LDA(dst, b, h)                                                                                                  \
;   _Pragma("unroll") for (int m = 0; m < 4; ++m) _Pragma("unroll") for (int k = 0; k < 2; ++k)                             \
;       dst[m][k] = *(const bf16x8*)((const char*)G_SA(b, h) + ((wr * 4 + m) * 2 + k) * 1024 + rdo)
; #define G_LDB(dst, b, h)                                                                                                  \
;   _Pragma("unroll") for (int n = 0; n < 2; ++n) _Pragma("unroll") for (int k = 0; k < 2; ++k)                             \
;       dst[n][k] = *(const bf16x8*)((const char*)G_SB(b, h) + ((wc * 2 + n) * 2 + k) * 1024 + rdo)
; #define G_WAIT_V(n) asm volatile("s_waitcnt vmcnt(" #n ")" ::: "memory")
; #define G_WAIT_L(n) asm volatile("s_waitcnt lgkmcnt(" #n ")" ::: "memory")
; #define G_BAR __builtin_amdgcn_s_barrier()
;     ...
;     G_LDB(B0, 1, 0); G_LDA(At, 1, 0); G_WAIT_V(2); G_BAR; G_WAIT_L(0); G_MMA(0, 0, At, B0); G_BAR;
;     G_LDB(B1, 1, 1); G_WAIT_V(0); G_BAR; G_WAIT_L(0); G_MMA(0, 1, At, B1); G_BAR;
;     G_LDA(At, 1, 1); G_BAR; G_WAIT_L(0); G_MMA(1, 0, At, B0); G_MMA(1, 1, At, B1); G_BAR;
;   }
;   if (wr == 0) G_BAR;
	s_waitcnt lgkmcnt(0)
	v_mfma_f32_16x16x32_bf16 v[126:129], v[186:189], v[130:133], v[126:129]
	v_mfma_f32_16x16x32_bf16 v[122:125], v[186:189], v[164:167], v[122:125]
	v_mfma_f32_16x16x32_bf16 v[118:121], v[194:197], v[130:133], v[118:121]
	v_mfma_f32_16x16x32_bf16 v[114:117], v[194:197], v[164:167], v[114:117]
	v_mfma_f32_16x16x32_bf16 v[110:113], v[202:205], v[130:133], v[110:113]
	v_mfma_f32_16x16x32_bf16 v[106:109], v[202:205], v[164:167], v[106:109]
	v_mfma_f32_16x16x32_bf16 v[102:105], v[210:213], v[130:133], v[102:105]
	v_mfma_f32_16x16x32_bf16 v[98:101], v[210:213], v[164:167], v[98:101]
	v_mfma_f32_16x16x32_bf16 v[158:161], v[190:193], v[154:157], v[126:129]
	v_mfma_f32_16x16x32_bf16 v[150:153], v[190:193], v[182:185], v[122:125]
	v_mfma_f32_16x16x32_bf16 v[146:149], v[198:201], v[154:157], v[118:121]
	v_mfma_f32_16x16x32_bf16 v[138:141], v[198:201], v[182:185], v[114:117]
	v_mfma_f32_16x16x32_bf16 v[134:137], v[206:209], v[154:157], v[110:113]
	v_mfma_f32_16x16x32_bf16 v[126:129], v[206:209], v[182:185], v[106:109]
	v_mfma_f32_16x16x32_bf16 v[122:125], v[214:217], v[154:157], v[102:105]
	v_mfma_f32_16x16x32_bf16 v[114:117], v[214:217], v[182:185], v[98:101]
	s_barrier
	ds_read_b128 v[118:121], v145
	ds_read_b128 v[218:221], v145 offset:1024
	ds_read_b128 v[222:225], v145 offset:2048
	ds_read_b128 v[226:229], v145 offset:3072
	s_waitcnt vmcnt(12)
	s_barrier
	s_waitcnt lgkmcnt(0)
	v_mfma_f32_16x16x32_bf16 v[94:97], v[186:189], v[118:121], v[94:97]
	v_mfma_f32_16x16x32_bf16 v[90:93], v[186:189], v[222:225], v[90:93]
	v_mfma_f32_16x16x32_bf16 v[86:89], v[194:197], v[118:121], v[86:89]
	v_mfma_f32_16x16x32_bf16 v[82:85], v[194:197], v[222:225], v[82:85]
	v_mfma_f32_16x16x32_bf16 v[78:81], v[202:205], v[118:121], v[78:81]
	v_mfma_f32_16x16x32_bf16 v[74:77], v[202:205], v[222:225], v[74:77]
	v_mfma_f32_16x16x32_bf16 v[70:73], v[210:213], v[118:121], v[70:73]
	v_mfma_f32_16x16x32_bf16 v[66:69], v[210:213], v[222:225], v[66:69]
	v_mfma_f32_16x16x32_bf16 v[110:113], v[190:193], v[218:221], v[94:97]
	v_mfma_f32_16x16x32_bf16 v[106:109], v[190:193], v[226:229], v[90:93]
	v_mfma_f32_16x16x32_bf16 v[102:105], v[198:201], v[218:221], v[86:89]
	v_mfma_f32_16x16x32_bf16 v[98:101], v[198:201], v[226:229], v[82:85]
	v_mfma_f32_16x16x32_bf16 v[94:97], v[206:209], v[218:221], v[78:81]
	v_mfma_f32_16x16x32_bf16 v[90:93], v[206:209], v[226:229], v[74:77]
	v_mfma_f32_16x16x32_bf16 v[86:89], v[214:217], v[218:221], v[70:73]
	v_mfma_f32_16x16x32_bf16 v[82:85], v[214:217], v[226:229], v[66:69]
	s_barrier
	ds_read_b128 v[186:189], v142 offset:49152
	ds_read_b128 v[190:193], v142 offset:50176
	ds_read_b128 v[194:197], v142 offset:51200
	ds_read_b128 v[198:201], v142 offset:52224
	ds_read_b128 v[202:205], v142 offset:53248
	ds_read_b128 v[206:209], v142 offset:54272
	ds_read_b128 v[210:213], v142 offset:55296
	ds_read_b128 v[142:145], v142 offset:56320
	s_barrier
	s_waitcnt lgkmcnt(0)
	v_mfma_f32_16x16x32_bf16 v[62:65], v[186:189], v[130:133], v[62:65]
	v_mfma_f32_16x16x32_bf16 v[58:61], v[186:189], v[164:167], v[58:61]
	v_mfma_f32_16x16x32_bf16 v[54:57], v[194:197], v[130:133], v[54:57]
	v_mfma_f32_16x16x32_bf16 v[50:53], v[194:197], v[164:167], v[50:53]
	v_mfma_f32_16x16x32_bf16 v[46:49], v[202:205], v[130:133], v[46:49]
	v_mfma_f32_16x16x32_bf16 v[42:45], v[202:205], v[164:167], v[42:45]
	v_mfma_f32_16x16x32_bf16 v[38:41], v[210:213], v[130:133], v[38:41]
	v_mfma_f32_16x16x32_bf16 v[34:37], v[210:213], v[164:167], v[34:37]
	v_mfma_f32_16x16x32_bf16 v[78:81], v[190:193], v[154:157], v[62:65]
	v_mfma_f32_16x16x32_bf16 v[74:77], v[190:193], v[182:185], v[58:61]
	v_mfma_f32_16x16x32_bf16 v[70:73], v[198:201], v[154:157], v[54:57]
	v_mfma_f32_16x16x32_bf16 v[66:69], v[198:201], v[182:185], v[50:53]
	v_mfma_f32_16x16x32_bf16 v[62:65], v[206:209], v[154:157], v[46:49]
	v_mfma_f32_16x16x32_bf16 v[58:61], v[206:209], v[182:185], v[42:45]
	v_mfma_f32_16x16x32_bf16 v[54:57], v[142:145], v[154:157], v[38:41]
	v_mfma_f32_16x16x32_bf16 v[50:53], v[142:145], v[182:185], v[34:37]
	v_mfma_f32_16x16x32_bf16 v[30:33], v[186:189], v[118:121], v[30:33]
	v_mfma_f32_16x16x32_bf16 v[26:29], v[186:189], v[222:225], v[26:29]
	v_mfma_f32_16x16x32_bf16 v[22:25], v[194:197], v[118:121], v[22:25]
	v_mfma_f32_16x16x32_bf16 v[18:21], v[194:197], v[222:225], v[18:21]
	v_mfma_f32_16x16x32_bf16 v[14:17], v[202:205], v[118:121], v[14:17]
	v_mfma_f32_16x16x32_bf16 v[10:13], v[202:205], v[222:225], v[10:13]
	v_mfma_f32_16x16x32_bf16 v[6:9], v[210:213], v[118:121], v[6:9]
	v_mfma_f32_16x16x32_bf16 v[2:5], v[210:213], v[222:225], v[2:5]
	v_mfma_f32_16x16x32_bf16 v[46:49], v[190:193], v[218:221], v[30:33]
	v_mfma_f32_16x16x32_bf16 v[38:41], v[190:193], v[226:229], v[26:29]
	v_mfma_f32_16x16x32_bf16 v[34:37], v[198:201], v[218:221], v[22:25]
	v_mfma_f32_16x16x32_bf16 v[26:29], v[198:201], v[226:229], v[18:21]
	v_mfma_f32_16x16x32_bf16 v[22:25], v[206:209], v[218:221], v[14:17]
	v_mfma_f32_16x16x32_bf16 v[14:17], v[206:209], v[226:229], v[10:13]
	v_mfma_f32_16x16x32_bf16 v[10:13], v[142:145], v[218:221], v[6:9]
	v_mfma_f32_16x16x32_bf16 v[2:5], v[142:145], v[226:229], v[2:5]
	v_cmp_gt_u32_e32 vcc, s67, v0
	s_barrier
	s_and_saveexec_b64 s[8:9], vcc
	s_cbranch_execz .LBB0_108
	s_barrier
